# attention: K/V tiles via LDS-DMA with XOR-swizzled dense images, key-permuted S rows, persistent -mrun seed, pk row sums, scalar loop
# speedup vs baseline: 1.1184x; 1.0135x over previous
.LBB0_618:
	v_cmp_lt_i32_e32 vcc, 7, v0
	s_and_saveexec_b64 s[2:3], vcc
	s_xor_b64 s[64:65], exec, s[2:3]
	s_cbranch_execz .LBB0_675
	v_cmp_lt_u32_e32 vcc, 15, v0
	s_and_saveexec_b64 s[2:3], vcc
	s_xor_b64 s[8:9], exec, s[2:3]
	s_cbranch_execz .LBB0_655
	v_add_u32_e32 v2, -16, v0
	v_lshrrev_b32_e32 v2, 1, v2
	v_sub_u32_e32 v14, 31, v2
	v_mov_b32_e32 v18, v198
	v_lshlrev_b32_e32 v15, 8, v14
	v_readlane_b32 s4, v240, 36
	v_and_b32_e32 v12, 31, v18
	v_ashrrev_i32_e32 v2, 1, v18
	v_and_b32_e32 v19, 1, v0
	v_readlane_b32 s2, v240, 21
	v_and_b32_e32 v16, 0xffffffe0, v2
	v_or3_b32 v2, s4, v15, v12
	v_bitop3_b32 v4, v19, 7, s2 bitop3:0xc8
	v_add_u32_e32 v5, v2, v16
	v_mov_b64_e32 v[2:3], s[72:73]
	v_bfe_u32 v13, v18, 5, 1
	v_mad_i64_i32 v[156:157], s[2:3], v5, s77, v[2:3]
	v_lshlrev_b32_e32 v2, 7, v4
	v_mov_b32_e32 v3, v1
	v_lshl_add_u64 v[2:3], v[156:157], 0, v[2:3]
	v_lshlrev_b32_e32 v158, 4, v13
	v_mov_b32_e32 v159, v1
	v_lshl_add_u64 v[2:3], v[2:3], 0, v[158:159]
	s_mov_b64 s[2:3], 0x1000
	v_lshlrev_b32_e32 v0, 6, v4
	v_lshl_add_u64 v[4:5], v[2:3], 0, s[2:3]
	v_add_co_u32_e32 v2, vcc, s78, v2
	s_mov_b64 s[2:3], 0x1400
	s_nop 0
	v_addc_co_u32_e32 v3, vcc, 0, v3, vcc
	global_load_dwordx4 v[112:115], v[4:5], off offset:32
	global_load_dwordx4 v[116:119], v[4:5], off offset:64
	global_load_dwordx4 v[120:123], v[2:3], off
	global_load_dwordx4 v[124:127], v[4:5], off offset:96
	v_lshl_add_u64 v[2:3], v[156:157], 0, v[0:1]
	v_lshl_add_u64 v[2:3], v[2:3], 0, v[158:159]
	v_lshl_add_u64 v[4:5], v[2:3], 0, s[2:3]
	v_add_co_u32_e32 v2, vcc, s78, v2
	s_nop 1
	v_addc_co_u32_e32 v3, vcc, 0, v3, vcc
	global_load_dwordx4 v[128:131], v[2:3], off offset:1024
	global_load_dwordx4 v[132:135], v[4:5], off offset:32
	v_mul_hi_i32 v2, v18, s50
	v_lshrrev_b32_e32 v3, 31, v2
	v_ashrrev_i32_e32 v2, 1, v2
	v_add_u32_e32 v17, v2, v3
	v_mul_lo_u32 v2, v17, 12
	v_sub_u32_e32 v2, v18, v2
	v_add_u32_e32 v160, s4, v17
	v_cmp_lt_i32_e64 s[2:3], 7, v2
	v_ashrrev_i32_e32 v161, 31, v160
	v_lshlrev_b32_e32 v162, 4, v2
	s_and_saveexec_b64 s[4:5], s[2:3]
	s_xor_b64 s[4:5], exec, s[4:5]
	v_mov_b64_e32 v[4:5], s[72:73]
	v_mad_i64_i32 v[4:5], s[6:7], v160, s77, v[4:5]
	v_mov_b32_e32 v163, v1
	v_lshl_add_u64 v[4:5], v[4:5], 0, v[162:163]
	v_lshl_add_u64 v[4:5], v[4:5], 0, s[74:75]
	s_or_saveexec_b64 s[4:5], s[4:5]
	v_lshlrev_b32_e32 v2, 3, v2
	v_lshlrev_b32_e32 v164, 1, v0
	v_ashrrev_i32_e32 v20, 31, v2
	s_xor_b64 exec, exec, s[4:5]
	v_lshlrev_b64 v[4:5], 10, v[160:161]
	v_lshl_add_u64 v[4:5], s[80:81], 0, v[4:5]
	v_mov_b32_e32 v165, v1
	v_lshl_add_u64 v[4:5], v[4:5], 0, v[164:165]
	v_mov_b32_e32 v3, v20
	v_lshl_add_u64 v[4:5], v[2:3], 1, v[4:5]
	s_or_b64 exec, exec, s[4:5]
	v_mov_b64_e32 v[136:137], v[4:5]
	v_lshlrev_b32_e32 v238, 2, v160
	v_and_b32_e32 v238, 0x30, v238
	v_xor_b32_e32 v136, v136, v238
	v_and_b32_e32 v239, 0x1c0, v198
	v_lshlrev_b32_e32 v239, 4, v239
	s_nop 1
	v_readfirstlane_b32 s14, v239
	s_mov_b32 m0, s14
	s_nop 0
	global_load_lds_dwordx4 v[136:137], off
	v_add_u32_e32 v3, 0x200, v18
	v_mul_hi_i32 v0, v3, s50
	v_lshrrev_b32_e32 v4, 31, v0
	v_ashrrev_i32_e32 v0, 1, v0
	v_add_u32_e32 v21, v0, v4
	v_mul_lo_u32 v0, v21, 12
	v_readlane_b32 s4, v240, 36
	v_sub_u32_e32 v0, v3, v0
	v_lshlrev_b32_e32 v168, 4, v0
	v_add_u32_e32 v166, s4, v21
	v_cmp_lt_i32_e64 s[4:5], 7, v0
	v_ashrrev_i32_e32 v167, 31, v166
	s_and_saveexec_b64 s[6:7], s[4:5]
	s_xor_b64 s[6:7], exec, s[6:7]
	v_mov_b64_e32 v[4:5], s[72:73]
	v_mad_i64_i32 v[4:5], s[10:11], v166, s77, v[4:5]
	v_mov_b32_e32 v169, v1
	v_lshl_add_u64 v[4:5], v[4:5], 0, v[168:169]
	v_lshl_add_u64 v[6:7], v[4:5], 0, s[74:75]
	s_or_saveexec_b64 s[6:7], s[6:7]
	v_lshlrev_b32_e32 v4, 3, v0
	v_ashrrev_i32_e32 v22, 31, v4
	s_xor_b64 exec, exec, s[6:7]
	v_lshlrev_b64 v[6:7], 10, v[166:167]
	v_lshl_add_u64 v[6:7], s[80:81], 0, v[6:7]
	v_mov_b32_e32 v165, v1
	v_lshl_add_u64 v[6:7], v[6:7], 0, v[164:165]
	v_mov_b32_e32 v5, v22
	v_lshl_add_u64 v[6:7], v[4:5], 1, v[6:7]
	s_or_b64 exec, exec, s[6:7]
	v_mov_b64_e32 v[138:139], v[6:7]
	v_lshlrev_b32_e32 v238, 2, v166
	v_and_b32_e32 v238, 0x30, v238
	v_xor_b32_e32 v138, v138, v238
	v_and_b32_e32 v239, 0x1c0, v198
	v_lshlrev_b32_e32 v239, 4, v239
	v_add_u32_e32 v239, 0x2000, v239
	s_nop 1
	v_readfirstlane_b32 s14, v239
	s_mov_b32 m0, s14
	s_nop 0
	global_load_lds_dwordx4 v[138:139], off
	v_add_u32_e32 v0, 0x400, v18
	v_mul_hi_i32 v5, v0, s50
	v_lshrrev_b32_e32 v6, 31, v5
	v_ashrrev_i32_e32 v5, 1, v5
	v_add_u32_e32 v23, v5, v6
	v_mul_lo_u32 v5, v23, 12
	v_readlane_b32 s6, v240, 36
	v_sub_u32_e32 v5, v0, v5
	v_lshlrev_b32_e32 v0, 3, v5
	v_add_u32_e32 v170, s6, v23
	v_cmp_lt_i32_e64 s[6:7], 7, v5
	v_ashrrev_i32_e32 v171, 31, v170
	v_lshlrev_b32_e32 v172, 4, v5
	s_and_saveexec_b64 s[10:11], s[6:7]
	s_xor_b64 s[10:11], exec, s[10:11]
	v_mov_b64_e32 v[6:7], s[72:73]
	v_mad_i64_i32 v[6:7], s[12:13], v170, s77, v[6:7]
	v_mov_b32_e32 v173, v1
	v_lshl_add_u64 v[6:7], v[6:7], 0, v[172:173]
	v_lshl_add_u64 v[10:11], v[6:7], 0, s[74:75]
	v_mov_b64_e32 v[6:7], v[0:1]
	s_or_saveexec_b64 s[10:11], s[10:11]
	v_mov_b64_e32 v[8:9], v[6:7]
	s_xor_b64 exec, exec, s[10:11]
	v_lshlrev_b64 v[6:7], 10, v[170:171]
	v_lshl_add_u64 v[6:7], s[80:81], 0, v[6:7]
	v_mov_b32_e32 v165, v1
	v_lshl_add_u64 v[8:9], v[6:7], 0, v[164:165]
	v_ashrrev_i32_e32 v7, 31, v0
	v_mov_b32_e32 v6, v0
	v_lshl_add_u64 v[10:11], v[6:7], 1, v[8:9]
	v_mov_b64_e32 v[8:9], v[0:1]
	s_or_b64 exec, exec, s[10:11]
	v_readlane_b32 s10, v240, 21
	v_mov_b64_e32 v[140:141], v[10:11]
	v_lshlrev_b32_e32 v238, 2, v170
	v_and_b32_e32 v238, 0x30, v238
	v_xor_b32_e32 v140, v140, v238
	v_and_b32_e32 v239, 0x1c0, v198
	v_lshlrev_b32_e32 v239, 4, v239
	v_add_u32_e32 v239, 0x4000, v239
	s_nop 1
	v_readfirstlane_b32 s14, v239
	s_mov_b32 m0, s14
	s_nop 0
	global_load_lds_dwordx4 v[140:141], off
	v_ashrrev_i32_e32 v10, 4, v18
	v_or_b32_e32 v0, s10, v19
	v_readlane_b32 s10, v240, 41
	v_lshlrev_b32_e32 v0, 20, v0
	v_readlane_b32 s11, v240, 42
	v_ashrrev_i32_e32 v11, 31, v10
	v_lshlrev_b64 v[26:27], 14, v[10:11]
	v_lshl_add_u64 v[24:25], s[10:11], 0, v[0:1]
	v_lshlrev_b32_e32 v0, 3, v18
	v_and_b32_e32 v161, 0x78, v0
	v_ashrrev_i32_e32 v18, 4, v3
	v_lshl_add_u64 v[26:27], v[24:25], 0, v[26:27]
	v_lshlrev_b32_e32 v0, 1, v161
	v_ashrrev_i32_e32 v19, 31, v18
	v_lshl_add_u64 v[174:175], v[26:27], 0, v[0:1]
	v_lshlrev_b64 v[26:27], 14, v[18:19]
	v_lshl_add_u64 v[24:25], v[24:25], 0, v[26:27]
	v_lshl_add_u64 v[176:177], v[24:25], 0, v[0:1]
	v_mov_b64_e32 v[142:143], v[174:175]
	v_and_b32_e32 v238, 0xf0, v198
	v_xor_b32_e32 v142, v142, v238
	v_and_b32_e32 v239, 0x1c0, v198
	v_lshlrev_b32_e32 v239, 4, v239
	v_add_u32_e32 v239, 0xc000, v239
	s_nop 1
	v_readfirstlane_b32 s14, v239
	s_mov_b32 m0, s14
	s_nop 0
	global_load_lds_dwordx4 v[142:143], off
	v_mov_b64_e32 v[144:145], v[176:177]
	v_and_b32_e32 v238, 0xf0, v198
	v_xor_b32_e32 v144, v144, v238
	v_and_b32_e32 v239, 0x1c0, v198
	v_lshlrev_b32_e32 v239, 4, v239
	v_add_u32_e32 v239, 0xe000, v239
	s_nop 1
	v_readfirstlane_b32 s14, v239
	s_mov_b32 m0, s14
	s_nop 0
	global_load_lds_dwordx4 v[144:145], off
	v_add_u32_e32 v0, v16, v15
	v_and_b32_e32 v3, 64, v202
	v_or_b32_e32 v171, v0, v12
	v_xor_b32_e32 v0, 32, v202
	v_add_u32_e32 v3, 64, v3
	v_cmp_lt_i32_e32 vcc, v0, v3
	v_mov_b32_e32 v3, v1
	v_mov_b32_e32 v165, v1
	v_mov_b32_e32 v5, v1
	v_lshlrev_b32_e32 v167, 1, v14
	v_lshl_add_u64 v[178:179], v[2:3], 1, s[72:73]
	v_lshl_add_u64 v[14:15], s[80:81], 0, v[164:165]
	v_mov_b32_e32 v3, v20
	v_lshl_add_u64 v[182:183], v[4:5], 1, s[72:73]
	v_mov_b32_e32 v5, v22
	v_cndmask_b32_e32 v0, v202, v0, vcc
	v_lshl_add_u64 v[180:181], v[2:3], 1, v[14:15]
	v_lshl_add_u64 v[184:185], v[4:5], 1, v[14:15]
	v_lshl_add_u64 v[188:189], v[6:7], 1, v[14:15]
	s_movk_i32 s10, 0x110
	v_mov_b32_e32 v14, v1
	v_mov_b32_e32 v15, v1
	v_lshlrev_b32_e32 v163, 3, v13
	v_lshlrev_b32_e32 v173, 2, v0
	v_lshl_add_u64 v[186:187], v[8:9], 1, s[72:73]
	v_lshlrev_b32_e32 v159, 2, v13
	v_mul_lo_u32 v165, v17, s51
	v_mul_lo_u32 v209, v21, s51
	v_mul_lo_u32 v210, v23, s51
	v_mul_lo_u32 v211, v10, s10
	v_mul_lo_u32 v212, v18, s10
	v_mul_u32_u24_e32 v213, 0xd0, v12
	v_mul_u32_u24_e32 v214, 0x110, v12
	v_mov_b32_e32 v0, v1
	v_mov_b32_e32 v2, v1
	v_mov_b32_e32 v3, v1
	v_mov_b32_e32 v4, v1
	v_mov_b32_e32 v5, v1
	v_mov_b32_e32 v6, v1
	v_mov_b32_e32 v7, v1
	v_mov_b32_e32 v8, v1
	v_mov_b32_e32 v9, v1
	v_mov_b32_e32 v10, v1
	v_mov_b32_e32 v11, v1
	v_mov_b32_e32 v12, v1
	v_mov_b32_e32 v13, v1
	v_mov_b64_e32 v[30:31], v[14:15]
	v_mov_b64_e32 v[46:47], v[14:15]
	v_add_u32_e32 v169, 2, v167
	s_mov_b32 s18, 0
	v_mov_b32_e32 v215, 0
	s_movk_i32 s52, 0x80
	s_mov_b64 s[10:11], 0
	v_mov_b64_e32 v[28:29], v[12:13]
	v_mov_b64_e32 v[26:27], v[10:11]
	v_mov_b64_e32 v[24:25], v[8:9]
	v_mov_b64_e32 v[22:23], v[6:7]
	v_mov_b64_e32 v[20:21], v[4:5]
	v_mov_b64_e32 v[18:19], v[2:3]
	v_mov_b64_e32 v[16:17], v[0:1]
	v_mov_b64_e32 v[44:45], v[12:13]
	v_mov_b64_e32 v[42:43], v[10:11]
	v_mov_b64_e32 v[40:41], v[8:9]
	v_mov_b64_e32 v[38:39], v[6:7]
	v_mov_b64_e32 v[36:37], v[4:5]
	v_mov_b64_e32 v[34:35], v[2:3]
	v_mov_b64_e32 v[32:33], v[0:1]
	v_mov_b32_e32 v0, 0
	s_lshl_b32 s12, s77, 7
	v_mov_b32_e32 v238, 0x20000
	v_mov_b32_e32 v239, s12
	v_cndmask_b32_e64 v146, v238, v239, s[2:3]
	v_mov_b32_e32 v147, 0
	v_cndmask_b32_e64 v148, v238, v239, s[4:5]
	v_mov_b32_e32 v149, 0
	v_cndmask_b32_e64 v150, v238, v239, s[6:7]
	v_mov_b32_e32 v151, 0
	v_and_b32_e32 v238, 31, v198
	v_bfe_u32 v239, v198, 5, 1
	v_and_b32_e32 v152, 0x13, v238
	v_and_b32_e32 v154, 8, v238
	v_lshrrev_b32_e32 v154, 1, v154
	v_or_b32_e32 v152, v152, v154
	v_and_b32_e32 v154, 4, v238
	v_lshlrev_b32_e32 v154, 1, v154
	v_or_b32_e32 v152, v152, v154
	v_bfe_u32 v154, v152, 2, 2
	v_xor_b32_e32 v154, v154, v239
	v_mul_u32_u24_e32 v152, 0xc0, v152
	v_lshl_add_u32 v152, v154, 4, v152
	v_and_b32_e32 v154, 15, v238
	v_xor_b32_e32 v154, v154, v239
	v_lshlrev_b32_e32 v153, 8, v238
	v_lshl_add_u32 v153, v154, 4, v153
	v_xor_b32_e32 v174, 0x80000000, v0
	v_mov_b32_e32 v175, v174
	v_mov_b32_e32 v176, v174
	v_mov_b32_e32 v177, v174
	v_mov_b32_e32 v178, v174
	v_mov_b32_e32 v179, v174
	v_mov_b32_e32 v180, v174
	v_mov_b32_e32 v181, v174
	v_mov_b32_e32 v182, v174
	v_mov_b32_e32 v183, v174
	v_mov_b32_e32 v184, v174
	v_mov_b32_e32 v185, v174
	v_mov_b32_e32 v186, v174
	v_mov_b32_e32 v187, v174
	v_mov_b32_e32 v188, v174
	v_mov_b32_e32 v189, v174
	v_readfirstlane_b32 s10, v169
	v_and_b32_e32 v238, 0x1c0, v198
	v_lshlrev_b32_e32 v238, 4, v238
	s_nop 1
	v_readfirstlane_b32 s11, v238
	s_branch .LBB0_634
.LBB0_633:
.LBB0_634:
	s_and_b32 s12, s18, 1
	s_mul_i32 s19, s12, 0x6000
	s_lshl_b32 s17, s12, 14
	s_add_i32 s17, s17, 0xc000
	s_add_i32 s16, s18, 1
	s_waitcnt vmcnt(0)
	s_barrier
	s_cmp_ge_u32 s16, s10
	s_cbranch_scc1 .Lattn_nodma_0
	s_xor_b32 s13, s12, 1
	s_mul_i32 s14, s13, 0x6000
	s_add_i32 s14, s14, s11
	s_lshl_b32 s15, s13, 14
	s_add_i32 s15, s15, s11
	s_add_i32 s15, s15, 0xc000
	s_movk_i32 s12, 0x100
	s_mov_b32 s13, 0
	s_add_i32 m0, s14, 0x0
	v_lshl_add_u64 v[136:137], v[136:137], 0, v[146:147]
	global_load_lds_dwordx4 v[136:137], off
	s_add_i32 m0, s14, 0x2000
	v_lshl_add_u64 v[138:139], v[138:139], 0, v[148:149]
	global_load_lds_dwordx4 v[138:139], off
	s_add_i32 m0, s14, 0x4000
	v_lshl_add_u64 v[140:141], v[140:141], 0, v[150:151]
	global_load_lds_dwordx4 v[140:141], off
	s_add_i32 m0, s15, 0x0
	v_lshl_add_u64 v[142:143], v[142:143], 0, s[12:13]
	global_load_lds_dwordx4 v[142:143], off
	s_add_i32 m0, s15, 0x2000
	v_lshl_add_u64 v[144:145], v[144:145], 0, s[12:13]
	global_load_lds_dwordx4 v[144:145], off
.Lattn_nodma_0:
	s_add_i32 s12, s18, 2
	s_cmp_ge_u32 s12, s10
	s_cbranch_scc1 .Lattn_slow_0
	v_add_u32_e32 v10, s19, v152
	v_xor_b32_e32 v154, 32, v10
	ds_read_b128 v[6:9], v10
	ds_read_b128 v[222:225], v154
	ds_read_b128 v[226:229], v10 offset:64
	ds_read_b128 v[230:233], v154 offset:64
	ds_read_b128 v[234:237], v10 offset:128
	ds_read_b128 v[242:245], v154 offset:128
	ds_read_b128 v[246:249], v10 offset:6144
	ds_read_b128 v[250:253], v154 offset:6144
	s_waitcnt lgkmcnt(7)
	v_mfma_f32_32x32x16_bf16 v[80:95], v[6:9], v[120:123], v[174:189]
	ds_read_b128 v[6:9], v10 offset:6208
	s_waitcnt lgkmcnt(7)
	v_mfma_f32_32x32x16_bf16 v[80:95], v[222:225], v[112:115], v[80:95]
	ds_read_b128 v[222:225], v154 offset:6208
	s_waitcnt lgkmcnt(7)
	v_mfma_f32_32x32x16_bf16 v[80:95], v[226:229], v[116:119], v[80:95]
	ds_read_b128 v[226:229], v10 offset:6272
	s_waitcnt lgkmcnt(7)
	v_mfma_f32_32x32x16_bf16 v[80:95], v[230:233], v[124:127], v[80:95]
	ds_read_b128 v[230:233], v154 offset:6272
	s_waitcnt lgkmcnt(7)
	v_mfma_f32_32x32x16_bf16 v[80:95], v[234:237], v[128:131], v[80:95]
	ds_read_b128 v[234:237], v10 offset:12288
	s_waitcnt lgkmcnt(7)
	v_mfma_f32_32x32x16_bf16 v[80:95], v[242:245], v[132:135], v[80:95]
	ds_read_b128 v[242:245], v154 offset:12288
	s_waitcnt lgkmcnt(7)
	v_mfma_f32_32x32x16_bf16 v[64:79], v[246:249], v[120:123], v[174:189]
	ds_read_b128 v[246:249], v10 offset:12352
	s_waitcnt lgkmcnt(7)
	v_mfma_f32_32x32x16_bf16 v[64:79], v[250:253], v[112:115], v[64:79]
	ds_read_b128 v[250:253], v154 offset:12352
	s_waitcnt lgkmcnt(7)
	v_mfma_f32_32x32x16_bf16 v[64:79], v[6:9], v[116:119], v[64:79]
	ds_read_b128 v[6:9], v10 offset:12416
	s_waitcnt lgkmcnt(7)
	v_mfma_f32_32x32x16_bf16 v[64:79], v[222:225], v[124:127], v[64:79]
	ds_read_b128 v[222:225], v154 offset:12416
	s_waitcnt lgkmcnt(7)
	v_mfma_f32_32x32x16_bf16 v[64:79], v[226:229], v[128:131], v[64:79]
	ds_read_b128 v[226:229], v10 offset:18432
	v_max3_f32 v3, v80, v81, v82
	v_max3_f32 v3, v3, v83, v84
	v_max3_f32 v3, v3, v85, v86
	v_max3_f32 v3, v3, v87, v88
	v_max3_f32 v3, v3, v89, v90
	s_waitcnt lgkmcnt(7)
	v_mfma_f32_32x32x16_bf16 v[64:79], v[230:233], v[132:135], v[64:79]
	ds_read_b128 v[230:233], v154 offset:18432
	v_max3_f32 v3, v3, v91, v92
	v_max3_f32 v3, v3, v93, v94
	v_max_f32_e32 v3, v3, v95
	v_exp_f32_e32 v80, v80
	v_exp_f32_e32 v81, v81
	s_waitcnt lgkmcnt(7)
	v_mfma_f32_32x32x16_bf16 v[96:111], v[234:237], v[120:123], v[174:189]
	ds_read_b128 v[234:237], v10 offset:18496
	v_exp_f32_e32 v82, v82
	v_exp_f32_e32 v83, v83
	v_mov_b64_e32 v[12:13], v[80:81]
	v_mov_b64_e32 v[14:15], v[82:83]
	v_exp_f32_e32 v84, v84
	s_waitcnt lgkmcnt(7)
	v_mfma_f32_32x32x16_bf16 v[96:111], v[242:245], v[112:115], v[96:111]
	ds_read_b128 v[242:245], v154 offset:18496
	v_exp_f32_e32 v85, v85
	v_exp_f32_e32 v86, v86
	v_exp_f32_e32 v87, v87
	v_pk_add_f32 v[12:13], v[12:13], v[84:85]
	v_pk_add_f32 v[14:15], v[14:15], v[86:87]
	s_waitcnt lgkmcnt(7)
	v_mfma_f32_32x32x16_bf16 v[96:111], v[246:249], v[116:119], v[96:111]
	ds_read_b128 v[246:249], v10 offset:18560
	v_cvt_pk_bf16_f32 v80, v80, v81
	v_cvt_pk_bf16_f32 v81, v82, v83
	v_cvt_pk_bf16_f32 v82, v84, v85
	v_cvt_pk_bf16_f32 v83, v86, v87
	v_exp_f32_e32 v88, v88
	s_waitcnt lgkmcnt(7)
	v_mfma_f32_32x32x16_bf16 v[96:111], v[250:253], v[124:127], v[96:111]
	ds_read_b128 v[250:253], v154 offset:18560
	v_exp_f32_e32 v89, v89
	v_exp_f32_e32 v90, v90
	v_exp_f32_e32 v91, v91
	v_pk_add_f32 v[12:13], v[12:13], v[88:89]
	v_pk_add_f32 v[14:15], v[14:15], v[90:91]
	s_waitcnt lgkmcnt(7)
	v_mfma_f32_32x32x16_bf16 v[96:111], v[6:9], v[128:131], v[96:111]
	v_add_u32_e32 v155, s17, v153
	v_exp_f32_e32 v92, v92
	v_exp_f32_e32 v93, v93
	v_exp_f32_e32 v94, v94
	v_exp_f32_e32 v95, v95
	v_pk_add_f32 v[12:13], v[12:13], v[92:93]
	s_waitcnt lgkmcnt(6)
	v_mfma_f32_32x32x16_bf16 v[96:111], v[222:225], v[132:135], v[96:111]
	ds_read_b128 v[222:225], v155
	v_pk_add_f32 v[14:15], v[14:15], v[94:95]
	v_cvt_pk_bf16_f32 v84, v88, v89
	v_cvt_pk_bf16_f32 v85, v90, v91
	v_cvt_pk_bf16_f32 v86, v92, v93
	v_cvt_pk_bf16_f32 v87, v94, v95
	s_waitcnt lgkmcnt(6)
	v_mfma_f32_32x32x16_bf16 v[48:63], v[226:229], v[120:123], v[174:189]
	ds_read_b128 v[226:229], v155 offset:8192
	v_max3_f32 v4, v64, v65, v66
	v_max3_f32 v4, v4, v67, v68
	v_max3_f32 v4, v4, v69, v70
	v_max3_f32 v4, v4, v71, v72
	v_max3_f32 v4, v4, v73, v74
	s_waitcnt lgkmcnt(6)
	v_mfma_f32_32x32x16_bf16 v[48:63], v[230:233], v[112:115], v[48:63]
	v_xor_b32_e32 v238, 32, v155
	ds_read_b128 v[230:233], v238
	v_max3_f32 v4, v4, v75, v76
	v_max3_f32 v4, v4, v77, v78
	v_max_f32_e32 v4, v4, v79
	v_exp_f32_e32 v64, v64
	v_exp_f32_e32 v65, v65
	s_waitcnt lgkmcnt(6)
	v_mfma_f32_32x32x16_bf16 v[48:63], v[234:237], v[116:119], v[48:63]
	ds_read_b128 v[234:237], v238 offset:8192
	v_exp_f32_e32 v66, v66
	v_exp_f32_e32 v67, v67
	v_pk_add_f32 v[12:13], v[12:13], v[64:65]
	v_pk_add_f32 v[14:15], v[14:15], v[66:67]
	v_exp_f32_e32 v68, v68
	s_waitcnt lgkmcnt(6)
	v_mfma_f32_32x32x16_bf16 v[48:63], v[242:245], v[124:127], v[48:63]
	v_xor_b32_e32 v239, 64, v155
	ds_read_b128 v[242:245], v239
	v_exp_f32_e32 v69, v69
	v_exp_f32_e32 v70, v70
	v_exp_f32_e32 v71, v71
	v_pk_add_f32 v[12:13], v[12:13], v[68:69]
	v_pk_add_f32 v[14:15], v[14:15], v[70:71]
	s_waitcnt lgkmcnt(6)
	v_mfma_f32_32x32x16_bf16 v[48:63], v[246:249], v[128:131], v[48:63]
	ds_read_b128 v[246:249], v239 offset:8192
	v_cvt_pk_bf16_f32 v64, v64, v65
	v_cvt_pk_bf16_f32 v65, v66, v67
	v_cvt_pk_bf16_f32 v66, v68, v69
	v_cvt_pk_bf16_f32 v67, v70, v71
	v_exp_f32_e32 v72, v72
	s_waitcnt lgkmcnt(6)
	v_mfma_f32_32x32x16_bf16 v[48:63], v[250:253], v[132:135], v[48:63]
	v_xor_b32_e32 v238, 96, v155
	ds_read_b128 v[250:253], v238
	v_exp_f32_e32 v73, v73
	v_exp_f32_e32 v74, v74
	v_exp_f32_e32 v75, v75
	v_pk_add_f32 v[12:13], v[12:13], v[72:73]
	v_pk_add_f32 v[14:15], v[14:15], v[74:75]
	s_waitcnt lgkmcnt(6)
	v_mfma_f32_32x32x16_bf16 v[32:47], v[222:225], v[80:83], v[32:47]
	v_exp_f32_e32 v76, v76
	v_exp_f32_e32 v77, v77
	v_exp_f32_e32 v78, v78
	s_waitcnt lgkmcnt(5)
	v_mfma_f32_32x32x16_bf16 v[16:31], v[226:229], v[80:83], v[16:31]
	ds_read_b128 v[222:225], v238 offset:8192
	v_xor_b32_e32 v239, 128, v155
	ds_read_b128 v[226:229], v239
	v_exp_f32_e32 v79, v79
	v_pk_add_f32 v[12:13], v[12:13], v[76:77]
	v_pk_add_f32 v[14:15], v[14:15], v[78:79]
	s_waitcnt lgkmcnt(6)
	v_mfma_f32_32x32x16_bf16 v[32:47], v[230:233], v[84:87], v[32:47]
	v_cvt_pk_bf16_f32 v68, v72, v73
	v_cvt_pk_bf16_f32 v69, v74, v75
	v_cvt_pk_bf16_f32 v70, v76, v77
	s_waitcnt lgkmcnt(5)
	v_mfma_f32_32x32x16_bf16 v[16:31], v[234:237], v[84:87], v[16:31]
	ds_read_b128 v[230:233], v239 offset:8192
	v_xor_b32_e32 v238, 160, v155
	ds_read_b128 v[234:237], v238
	v_cvt_pk_bf16_f32 v71, v78, v79
	s_waitcnt lgkmcnt(6)
	v_mfma_f32_32x32x16_bf16 v[32:47], v[242:245], v[64:67], v[32:47]
	v_max3_f32 v5, v96, v97, v98
	v_max3_f32 v5, v5, v99, v100
	v_max3_f32 v5, v5, v101, v102
	v_max3_f32 v5, v5, v103, v104
	v_max3_f32 v5, v5, v105, v106
	v_max3_f32 v5, v5, v107, v108
	v_max3_f32 v5, v5, v109, v110
	v_max_f32_e32 v5, v5, v111
	v_exp_f32_e32 v96, v96
	v_exp_f32_e32 v97, v97
	s_waitcnt lgkmcnt(5)
	v_mfma_f32_32x32x16_bf16 v[16:31], v[246:249], v[64:67], v[16:31]
	ds_read_b128 v[242:245], v238 offset:8192
	v_xor_b32_e32 v239, 192, v155
	ds_read_b128 v[246:249], v239
	v_exp_f32_e32 v98, v98
	v_exp_f32_e32 v99, v99
	v_pk_add_f32 v[12:13], v[12:13], v[96:97]
	v_pk_add_f32 v[14:15], v[14:15], v[98:99]
	v_exp_f32_e32 v100, v100
	v_exp_f32_e32 v101, v101
	v_exp_f32_e32 v102, v102
	v_exp_f32_e32 v103, v103
	v_pk_add_f32 v[12:13], v[12:13], v[100:101]
	v_pk_add_f32 v[14:15], v[14:15], v[102:103]
	s_waitcnt lgkmcnt(6)
	v_mfma_f32_32x32x16_bf16 v[32:47], v[250:253], v[68:71], v[32:47]
	v_cvt_pk_bf16_f32 v96, v96, v97
	v_cvt_pk_bf16_f32 v97, v98, v99
	v_cvt_pk_bf16_f32 v98, v100, v101
	v_cvt_pk_bf16_f32 v99, v102, v103
	v_exp_f32_e32 v104, v104
	v_exp_f32_e32 v105, v105
	v_exp_f32_e32 v106, v106
	v_exp_f32_e32 v107, v107
	v_pk_add_f32 v[12:13], v[12:13], v[104:105]
	v_pk_add_f32 v[14:15], v[14:15], v[106:107]
	s_waitcnt lgkmcnt(5)
	v_mfma_f32_32x32x16_bf16 v[16:31], v[222:225], v[68:71], v[16:31]
	ds_read_b128 v[250:253], v239 offset:8192
	v_xor_b32_e32 v238, 224, v155
	ds_read_b128 v[222:225], v238
	v_exp_f32_e32 v108, v108
	v_exp_f32_e32 v109, v109
	v_exp_f32_e32 v110, v110
	v_exp_f32_e32 v111, v111
	v_pk_add_f32 v[12:13], v[12:13], v[108:109]
	v_pk_add_f32 v[14:15], v[14:15], v[110:111]
	v_cvt_pk_bf16_f32 v100, v104, v105
	v_cvt_pk_bf16_f32 v101, v106, v107
	v_cvt_pk_bf16_f32 v102, v108, v109
	v_cvt_pk_bf16_f32 v103, v110, v111
	s_waitcnt lgkmcnt(6)
	v_mfma_f32_32x32x16_bf16 v[32:47], v[226:229], v[96:99], v[32:47]
	v_max3_f32 v2, v48, v49, v50
	v_max3_f32 v2, v2, v51, v52
	v_max3_f32 v2, v2, v53, v54
	v_max3_f32 v2, v2, v55, v56
	v_max3_f32 v2, v2, v57, v58
	v_max3_f32 v2, v2, v59, v60
	v_max3_f32 v2, v2, v61, v62
	v_max_f32_e32 v2, v2, v63
	v_exp_f32_e32 v48, v48
	v_exp_f32_e32 v49, v49
	s_waitcnt lgkmcnt(5)
	v_mfma_f32_32x32x16_bf16 v[16:31], v[230:233], v[96:99], v[16:31]
	ds_read_b128 v[226:229], v238 offset:8192
	v_exp_f32_e32 v50, v50
	v_exp_f32_e32 v51, v51
	v_pk_add_f32 v[12:13], v[12:13], v[48:49]
	v_pk_add_f32 v[14:15], v[14:15], v[50:51]
	v_exp_f32_e32 v52, v52
	v_exp_f32_e32 v53, v53
	v_exp_f32_e32 v54, v54
	v_exp_f32_e32 v55, v55
	v_pk_add_f32 v[12:13], v[12:13], v[52:53]
	v_pk_add_f32 v[14:15], v[14:15], v[54:55]
	s_waitcnt lgkmcnt(5)
	v_mfma_f32_32x32x16_bf16 v[32:47], v[234:237], v[100:103], v[32:47]
	v_cvt_pk_bf16_f32 v48, v48, v49
	v_cvt_pk_bf16_f32 v49, v50, v51
	v_cvt_pk_bf16_f32 v50, v52, v53
	v_cvt_pk_bf16_f32 v51, v54, v55
	v_exp_f32_e32 v56, v56
	v_exp_f32_e32 v57, v57
	v_exp_f32_e32 v58, v58
	v_exp_f32_e32 v59, v59
	v_pk_add_f32 v[12:13], v[12:13], v[56:57]
	v_pk_add_f32 v[14:15], v[14:15], v[58:59]
	s_waitcnt lgkmcnt(4)
	v_mfma_f32_32x32x16_bf16 v[16:31], v[242:245], v[100:103], v[16:31]
	v_exp_f32_e32 v60, v60
	v_exp_f32_e32 v61, v61
	v_exp_f32_e32 v62, v62
	v_exp_f32_e32 v63, v63
	v_pk_add_f32 v[12:13], v[12:13], v[60:61]
	v_pk_add_f32 v[14:15], v[14:15], v[62:63]
	v_cvt_pk_bf16_f32 v52, v56, v57
	v_cvt_pk_bf16_f32 v53, v58, v59
	v_cvt_pk_bf16_f32 v54, v60, v61
	v_cvt_pk_bf16_f32 v55, v62, v63
	s_waitcnt lgkmcnt(3)
	v_mfma_f32_32x32x16_bf16 v[32:47], v[246:249], v[48:51], v[32:47]
	s_waitcnt lgkmcnt(2)
	v_mfma_f32_32x32x16_bf16 v[16:31], v[250:253], v[48:51], v[16:31]
	s_waitcnt lgkmcnt(1)
	v_mfma_f32_32x32x16_bf16 v[32:47], v[222:225], v[52:55], v[32:47]
	s_waitcnt lgkmcnt(0)
	v_mfma_f32_32x32x16_bf16 v[16:31], v[226:229], v[52:55], v[16:31]
	v_add_f32_e32 v12, v12, v13
	v_add_f32_e32 v14, v14, v15
	v_max3_f32 v2, v2, v3, v4
	v_add_f32_e32 v12, v12, v14
	v_max_f32_e32 v2, v2, v5
	v_add_f32_e32 v215, v215, v12
	v_mov_b32_e32 v3, v2
	s_nop 1
	v_permlane32_swap_b32_e32 v2, v3
	v_max_f32_e32 v2, v2, v3
	v_cmp_lt_f32_e32 vcc, 0, v2
	s_cbranch_vccz .Lattn_fnr_0
	s_nop 7
	s_nop 3
	v_max_f32_e32 v2, 0, v2
	v_exp_f32_e64 v4, -v2
	v_add_f32_e32 v0, v0, v2
	s_nop 0
	v_mul_f32_e32 v215, v215, v4
	v_mul_f32_e32 v16, v16, v4
	v_mul_f32_e32 v17, v17, v4
	v_mul_f32_e32 v18, v18, v4
	v_mul_f32_e32 v19, v19, v4
	v_mul_f32_e32 v20, v20, v4
	v_mul_f32_e32 v21, v21, v4
	v_mul_f32_e32 v22, v22, v4
	v_mul_f32_e32 v23, v23, v4
	v_mul_f32_e32 v24, v24, v4
	v_mul_f32_e32 v25, v25, v4
	v_mul_f32_e32 v26, v26, v4
	v_mul_f32_e32 v27, v27, v4
	v_mul_f32_e32 v28, v28, v4
	v_mul_f32_e32 v29, v29, v4
	v_mul_f32_e32 v30, v30, v4
	v_mul_f32_e32 v31, v31, v4
	v_mul_f32_e32 v32, v32, v4
	v_mul_f32_e32 v33, v33, v4
	v_mul_f32_e32 v34, v34, v4
	v_mul_f32_e32 v35, v35, v4
	v_mul_f32_e32 v36, v36, v4
	v_mul_f32_e32 v37, v37, v4
	v_mul_f32_e32 v38, v38, v4
	v_mul_f32_e32 v39, v39, v4
	v_mul_f32_e32 v40, v40, v4
	v_mul_f32_e32 v41, v41, v4
	v_mul_f32_e32 v42, v42, v4
	v_mul_f32_e32 v43, v43, v4
	v_mul_f32_e32 v44, v44, v4
	v_mul_f32_e32 v45, v45, v4
	v_mul_f32_e32 v46, v46, v4
	v_mul_f32_e32 v47, v47, v4
	v_xor_b32_e32 v174, 0x80000000, v0
	v_mov_b32_e32 v175, v174
	v_mov_b32_e32 v176, v174
	v_mov_b32_e32 v177, v174
	v_mov_b32_e32 v178, v174
	v_mov_b32_e32 v179, v174
	v_mov_b32_e32 v180, v174
	v_mov_b32_e32 v181, v174
	v_mov_b32_e32 v182, v174
	v_mov_b32_e32 v183, v174
	v_mov_b32_e32 v184, v174
	v_mov_b32_e32 v185, v174
	v_mov_b32_e32 v186, v174
	v_mov_b32_e32 v187, v174
	v_mov_b32_e32 v188, v174
	v_mov_b32_e32 v189, v174
.Lattn_fnr_0:
	s_addk_i32 s52, 0x80
	s_mov_b32 s18, s16
	s_cmp_lt_u32 s18, s10
	s_cbranch_scc1 .LBB0_634
	s_branch .LBB0_652
.Lattn_slow_0:
	v_add_u32_e32 v10, s19, v152
	v_xor_b32_e32 v154, 32, v10
	ds_read_b128 v[6:9], v10
	ds_read_b128 v[222:225], v154
	ds_read_b128 v[226:229], v10 offset:64
	ds_read_b128 v[230:233], v154 offset:64
	ds_read_b128 v[234:237], v10 offset:128
	ds_read_b128 v[242:245], v154 offset:128
	ds_read_b128 v[246:249], v10 offset:6144
	ds_read_b128 v[250:253], v154 offset:6144
	s_waitcnt lgkmcnt(7)
	v_mfma_f32_32x32x16_bf16 v[80:95], v[6:9], v[120:123], v[174:189]
	ds_read_b128 v[6:9], v10 offset:6208
	s_waitcnt lgkmcnt(7)
	v_mfma_f32_32x32x16_bf16 v[80:95], v[222:225], v[112:115], v[80:95]
	ds_read_b128 v[222:225], v154 offset:6208
	s_waitcnt lgkmcnt(7)
	v_mfma_f32_32x32x16_bf16 v[80:95], v[226:229], v[116:119], v[80:95]
	ds_read_b128 v[226:229], v10 offset:6272
	s_waitcnt lgkmcnt(7)
	v_mfma_f32_32x32x16_bf16 v[80:95], v[230:233], v[124:127], v[80:95]
	ds_read_b128 v[230:233], v154 offset:6272
	s_waitcnt lgkmcnt(7)
	v_mfma_f32_32x32x16_bf16 v[80:95], v[234:237], v[128:131], v[80:95]
	ds_read_b128 v[234:237], v10 offset:12288
	s_waitcnt lgkmcnt(7)
	v_mfma_f32_32x32x16_bf16 v[80:95], v[242:245], v[132:135], v[80:95]
	ds_read_b128 v[242:245], v154 offset:12288
	s_waitcnt lgkmcnt(7)
	v_mfma_f32_32x32x16_bf16 v[64:79], v[246:249], v[120:123], v[174:189]
	ds_read_b128 v[246:249], v10 offset:12352
	s_waitcnt lgkmcnt(7)
	v_mfma_f32_32x32x16_bf16 v[64:79], v[250:253], v[112:115], v[64:79]
	ds_read_b128 v[250:253], v154 offset:12352
	s_waitcnt lgkmcnt(7)
	v_mfma_f32_32x32x16_bf16 v[64:79], v[6:9], v[116:119], v[64:79]
	ds_read_b128 v[6:9], v10 offset:12416
	s_waitcnt lgkmcnt(7)
	v_mfma_f32_32x32x16_bf16 v[64:79], v[222:225], v[124:127], v[64:79]
	ds_read_b128 v[222:225], v154 offset:12416
	s_waitcnt lgkmcnt(7)
	v_mfma_f32_32x32x16_bf16 v[64:79], v[226:229], v[128:131], v[64:79]
	ds_read_b128 v[226:229], v10 offset:18432
	s_waitcnt lgkmcnt(7)
	v_mfma_f32_32x32x16_bf16 v[64:79], v[230:233], v[132:135], v[64:79]
	ds_read_b128 v[230:233], v154 offset:18432
	s_waitcnt lgkmcnt(7)
	v_mfma_f32_32x32x16_bf16 v[96:111], v[234:237], v[120:123], v[174:189]
	ds_read_b128 v[234:237], v10 offset:18496
	s_waitcnt lgkmcnt(7)
	v_mfma_f32_32x32x16_bf16 v[96:111], v[242:245], v[112:115], v[96:111]
	ds_read_b128 v[242:245], v154 offset:18496
	s_waitcnt lgkmcnt(7)
	v_mfma_f32_32x32x16_bf16 v[96:111], v[246:249], v[116:119], v[96:111]
	ds_read_b128 v[246:249], v10 offset:18560
	s_waitcnt lgkmcnt(7)
	v_mfma_f32_32x32x16_bf16 v[96:111], v[250:253], v[124:127], v[96:111]
	ds_read_b128 v[250:253], v154 offset:18560
	s_waitcnt lgkmcnt(7)
	v_mfma_f32_32x32x16_bf16 v[96:111], v[6:9], v[128:131], v[96:111]
	s_waitcnt lgkmcnt(6)
	v_mfma_f32_32x32x16_bf16 v[96:111], v[222:225], v[132:135], v[96:111]
	s_waitcnt lgkmcnt(5)
	v_mfma_f32_32x32x16_bf16 v[48:63], v[226:229], v[120:123], v[174:189]
	s_waitcnt lgkmcnt(4)
	v_mfma_f32_32x32x16_bf16 v[48:63], v[230:233], v[112:115], v[48:63]
	s_waitcnt lgkmcnt(3)
	v_mfma_f32_32x32x16_bf16 v[48:63], v[234:237], v[116:119], v[48:63]
	s_waitcnt lgkmcnt(2)
	v_mfma_f32_32x32x16_bf16 v[48:63], v[242:245], v[124:127], v[48:63]
	s_waitcnt lgkmcnt(1)
	v_mfma_f32_32x32x16_bf16 v[48:63], v[246:249], v[128:131], v[48:63]
	s_waitcnt lgkmcnt(0)
	v_mfma_f32_32x32x16_bf16 v[48:63], v[250:253], v[132:135], v[48:63]
	v_add_u32_e32 v155, s17, v153
	ds_read_b128 v[222:225], v155
	ds_read_b128 v[226:229], v155 offset:8192
	v_xor_b32_e32 v238, 32, v155
	ds_read_b128 v[230:233], v238
	ds_read_b128 v[234:237], v238 offset:8192
	v_xor_b32_e32 v239, 64, v155
	ds_read_b128 v[242:245], v239
	ds_read_b128 v[246:249], v239 offset:8192
	v_xor_b32_e32 v238, 96, v155
	ds_read_b128 v[250:253], v238
	v_bfe_u32 v2, v198, 5, 1
	v_lshl_add_u32 v2, v2, 3, s52
	v_sub_u32_e32 v2, v171, v2
	v_add_u32_e32 v2, 0x80, v2
	v_add_u32_e32 v3, 0, v2
	v_cmp_le_i32_e64 vcc, 0, v3
	v_cmp_le_i32_e64 s[12:13], 1, v3
	v_cmp_le_i32_e64 s[14:15], 2, v3
	v_cndmask_b32_e64 v80, v203, v80, vcc
	v_cmp_le_i32_e64 vcc, 3, v3
	v_cndmask_b32_e64 v81, v203, v81, s[12:13]
	v_cmp_le_i32_e64 s[12:13], 4, v3
	v_cndmask_b32_e64 v82, v203, v82, s[14:15]
	v_cmp_le_i32_e64 s[14:15], 5, v3
	v_cndmask_b32_e64 v83, v203, v83, vcc
	v_cmp_le_i32_e64 vcc, 6, v3
	v_cndmask_b32_e64 v84, v203, v84, s[12:13]
	v_cmp_le_i32_e64 s[12:13], 7, v3
	v_cndmask_b32_e64 v85, v203, v85, s[14:15]
	v_add_u32_e32 v4, -16, v2
	v_cmp_le_i32_e64 s[14:15], 0, v4
	v_cndmask_b32_e64 v86, v203, v86, vcc
	v_cmp_le_i32_e64 vcc, 1, v4
	v_cndmask_b32_e64 v87, v203, v87, s[12:13]
	v_cmp_le_i32_e64 s[12:13], 2, v4
	v_cndmask_b32_e64 v88, v203, v88, s[14:15]
	v_cmp_le_i32_e64 s[14:15], 3, v4
	v_cndmask_b32_e64 v89, v203, v89, vcc
	v_cmp_le_i32_e64 vcc, 4, v4
	v_cndmask_b32_e64 v90, v203, v90, s[12:13]
	v_cmp_le_i32_e64 s[12:13], 5, v4
	v_cndmask_b32_e64 v91, v203, v91, s[14:15]
	v_cmp_le_i32_e64 s[14:15], 6, v4
	v_cndmask_b32_e64 v92, v203, v92, vcc
	v_cmp_le_i32_e64 vcc, 7, v4
	v_cndmask_b32_e64 v93, v203, v93, s[12:13]
	v_add_u32_e32 v3, 0xffffffe0, v2
	v_cmp_le_i32_e64 s[12:13], 0, v3
	v_cndmask_b32_e64 v94, v203, v94, s[14:15]
	v_cmp_le_i32_e64 s[14:15], 1, v3
	v_cndmask_b32_e64 v95, v203, v95, vcc
	v_cmp_le_i32_e64 vcc, 2, v3
	v_cndmask_b32_e64 v64, v203, v64, s[12:13]
	v_cmp_le_i32_e64 s[12:13], 3, v3
	v_cndmask_b32_e64 v65, v203, v65, s[14:15]
	v_cmp_le_i32_e64 s[14:15], 4, v3
	v_cndmask_b32_e64 v66, v203, v66, vcc
	v_cmp_le_i32_e64 vcc, 5, v3
	v_cndmask_b32_e64 v67, v203, v67, s[12:13]
	v_cmp_le_i32_e64 s[12:13], 6, v3
	v_cndmask_b32_e64 v68, v203, v68, s[14:15]
	v_cmp_le_i32_e64 s[14:15], 7, v3
	v_cndmask_b32_e64 v69, v203, v69, vcc
	v_add_u32_e32 v4, 0xffffffd0, v2
	v_cmp_le_i32_e64 vcc, 0, v4
	v_cndmask_b32_e64 v70, v203, v70, s[12:13]
	v_cmp_le_i32_e64 s[12:13], 1, v4
	v_cndmask_b32_e64 v71, v203, v71, s[14:15]
	v_cmp_le_i32_e64 s[14:15], 2, v4
	v_cndmask_b32_e64 v72, v203, v72, vcc
	v_cmp_le_i32_e64 vcc, 3, v4
	v_cndmask_b32_e64 v73, v203, v73, s[12:13]
	v_cmp_le_i32_e64 s[12:13], 4, v4
	v_cndmask_b32_e64 v74, v203, v74, s[14:15]
	v_cmp_le_i32_e64 s[14:15], 5, v4
	v_cndmask_b32_e64 v75, v203, v75, vcc
	v_cmp_le_i32_e64 vcc, 6, v4
	v_cndmask_b32_e64 v76, v203, v76, s[12:13]
	v_cmp_le_i32_e64 s[12:13], 7, v4
	v_cndmask_b32_e64 v77, v203, v77, s[14:15]
	v_add_u32_e32 v3, 0xffffffc0, v2
	v_cmp_le_i32_e64 s[14:15], 0, v3
	v_cndmask_b32_e64 v78, v203, v78, vcc
	v_cmp_le_i32_e64 vcc, 1, v3
	v_cndmask_b32_e64 v79, v203, v79, s[12:13]
	v_cmp_le_i32_e64 s[12:13], 2, v3
	v_cndmask_b32_e64 v96, v203, v96, s[14:15]
	v_cmp_le_i32_e64 s[14:15], 3, v3
	v_cndmask_b32_e64 v97, v203, v97, vcc
	v_cmp_le_i32_e64 vcc, 4, v3
	v_cndmask_b32_e64 v98, v203, v98, s[12:13]
	v_cmp_le_i32_e64 s[12:13], 5, v3
	v_cndmask_b32_e64 v99, v203, v99, s[14:15]
	v_cmp_le_i32_e64 s[14:15], 6, v3
	v_cndmask_b32_e64 v100, v203, v100, vcc
	v_cmp_le_i32_e64 vcc, 7, v3
	v_cndmask_b32_e64 v101, v203, v101, s[12:13]
	v_add_u32_e32 v4, 0xffffffb0, v2
	v_cmp_le_i32_e64 s[12:13], 0, v4
	v_cndmask_b32_e64 v102, v203, v102, s[14:15]
	v_cmp_le_i32_e64 s[14:15], 1, v4
	v_cndmask_b32_e64 v103, v203, v103, vcc
	v_cmp_le_i32_e64 vcc, 2, v4
	v_cndmask_b32_e64 v104, v203, v104, s[12:13]
	v_cmp_le_i32_e64 s[12:13], 3, v4
	v_cndmask_b32_e64 v105, v203, v105, s[14:15]
	v_cmp_le_i32_e64 s[14:15], 4, v4
	v_cndmask_b32_e64 v106, v203, v106, vcc
	v_cmp_le_i32_e64 vcc, 5, v4
	v_cndmask_b32_e64 v107, v203, v107, s[12:13]
	v_cmp_le_i32_e64 s[12:13], 6, v4
	v_cndmask_b32_e64 v108, v203, v108, s[14:15]
	v_cmp_le_i32_e64 s[14:15], 7, v4
	v_cndmask_b32_e64 v109, v203, v109, vcc
	v_add_u32_e32 v3, 0xffffffa0, v2
	v_cmp_le_i32_e64 vcc, 0, v3
	v_cndmask_b32_e64 v110, v203, v110, s[12:13]
	v_cmp_le_i32_e64 s[12:13], 1, v3
	v_cndmask_b32_e64 v111, v203, v111, s[14:15]
	v_cmp_le_i32_e64 s[14:15], 2, v3
	v_cndmask_b32_e64 v48, v203, v48, vcc
	v_cmp_le_i32_e64 vcc, 3, v3
	v_cndmask_b32_e64 v49, v203, v49, s[12:13]
	v_cmp_le_i32_e64 s[12:13], 4, v3
	v_cndmask_b32_e64 v50, v203, v50, s[14:15]
	v_cmp_le_i32_e64 s[14:15], 5, v3
	v_cndmask_b32_e64 v51, v203, v51, vcc
	v_cmp_le_i32_e64 vcc, 6, v3
	v_cndmask_b32_e64 v52, v203, v52, s[12:13]
	v_cmp_le_i32_e64 s[12:13], 7, v3
	v_cndmask_b32_e64 v53, v203, v53, s[14:15]
	v_add_u32_e32 v4, 0xffffff90, v2
	v_cmp_le_i32_e64 s[14:15], 0, v4
	v_cndmask_b32_e64 v54, v203, v54, vcc
	v_cmp_le_i32_e64 vcc, 1, v4
	v_cndmask_b32_e64 v55, v203, v55, s[12:13]
	v_cmp_le_i32_e64 s[12:13], 2, v4
	v_cndmask_b32_e64 v56, v203, v56, s[14:15]
	v_cmp_le_i32_e64 s[14:15], 3, v4
	v_cndmask_b32_e64 v57, v203, v57, vcc
	v_cmp_le_i32_e64 vcc, 4, v4
	v_cndmask_b32_e64 v58, v203, v58, s[12:13]
	v_cmp_le_i32_e64 s[12:13], 5, v4
	v_cndmask_b32_e64 v59, v203, v59, s[14:15]
	v_cmp_le_i32_e64 s[14:15], 6, v4
	v_cndmask_b32_e64 v60, v203, v60, vcc
	v_cmp_le_i32_e64 vcc, 7, v4
	v_cndmask_b32_e64 v61, v203, v61, s[12:13]
	v_cndmask_b32_e64 v62, v203, v62, s[14:15]
	v_cndmask_b32_e64 v63, v203, v63, vcc
	v_max_f32_e32 v2, v81, v81
	v_max_f32_e32 v3, v80, v80
	v_max_f32_e32 v2, v3, v2
	v_max3_f32 v2, v2, v82, v83
	v_max3_f32 v2, v2, v84, v85
	v_max3_f32 v2, v2, v86, v87
	v_max3_f32 v2, v2, v88, v89
	v_max3_f32 v2, v2, v90, v91
	v_max3_f32 v2, v2, v92, v93
	v_max3_f32 v2, v2, v94, v95
	v_max3_f32 v2, v2, v64, v65
	v_max3_f32 v2, v2, v66, v67
	v_max3_f32 v2, v2, v68, v69
	v_max3_f32 v2, v2, v70, v71
	v_max3_f32 v2, v2, v72, v73
	v_max3_f32 v2, v2, v74, v75
	v_max3_f32 v2, v2, v76, v77
	v_max3_f32 v2, v2, v78, v79
	v_max3_f32 v2, v2, v96, v97
	v_max3_f32 v2, v2, v98, v99
	v_max3_f32 v2, v2, v100, v101
	v_max3_f32 v2, v2, v102, v103
	v_max3_f32 v2, v2, v104, v105
	v_max3_f32 v2, v2, v106, v107
	v_max3_f32 v2, v2, v108, v109
	v_max3_f32 v2, v2, v110, v111
	v_max3_f32 v2, v2, v48, v49
	v_max3_f32 v2, v2, v50, v51
	v_max3_f32 v2, v2, v52, v53
	v_max3_f32 v2, v2, v54, v55
	v_max3_f32 v2, v2, v56, v57
	v_max3_f32 v2, v2, v58, v59
	v_max3_f32 v2, v2, v60, v61
	v_max3_f32 v2, v2, v62, v63
	v_mov_b32_e32 v3, v2
	s_nop 1
	v_permlane32_swap_b32_e32 v2, v3
	v_max_f32_e32 v2, v2, v3
	v_cmp_lt_f32_e32 vcc, 0, v2
	s_cbranch_vccz .Lattn_snr_0
	v_max_f32_e32 v2, v2, v2
	v_max_f32_e32 v2, 0, v2
	v_exp_f32_e64 v4, -v2
	v_add_f32_e32 v0, v0, v2
	v_pk_add_f32 v[80:81], v[80:81], v[2:3] op_sel_hi:[1,0] neg_lo:[0,1] neg_hi:[0,1]
	v_pk_add_f32 v[64:65], v[64:65], v[2:3] op_sel_hi:[1,0] neg_lo:[0,1] neg_hi:[0,1]
	v_pk_add_f32 v[96:97], v[96:97], v[2:3] op_sel_hi:[1,0] neg_lo:[0,1] neg_hi:[0,1]
	v_pk_add_f32 v[48:49], v[48:49], v[2:3] op_sel_hi:[1,0] neg_lo:[0,1] neg_hi:[0,1]
	v_pk_add_f32 v[82:83], v[82:83], v[2:3] op_sel_hi:[1,0] neg_lo:[0,1] neg_hi:[0,1]
	v_pk_add_f32 v[66:67], v[66:67], v[2:3] op_sel_hi:[1,0] neg_lo:[0,1] neg_hi:[0,1]
	v_pk_add_f32 v[98:99], v[98:99], v[2:3] op_sel_hi:[1,0] neg_lo:[0,1] neg_hi:[0,1]
	v_pk_add_f32 v[50:51], v[50:51], v[2:3] op_sel_hi:[1,0] neg_lo:[0,1] neg_hi:[0,1]
	v_pk_add_f32 v[84:85], v[84:85], v[2:3] op_sel_hi:[1,0] neg_lo:[0,1] neg_hi:[0,1]
	v_pk_add_f32 v[68:69], v[68:69], v[2:3] op_sel_hi:[1,0] neg_lo:[0,1] neg_hi:[0,1]
	v_pk_add_f32 v[100:101], v[100:101], v[2:3] op_sel_hi:[1,0] neg_lo:[0,1] neg_hi:[0,1]
	v_pk_add_f32 v[52:53], v[52:53], v[2:3] op_sel_hi:[1,0] neg_lo:[0,1] neg_hi:[0,1]
	v_pk_add_f32 v[86:87], v[86:87], v[2:3] op_sel_hi:[1,0] neg_lo:[0,1] neg_hi:[0,1]
	v_pk_add_f32 v[70:71], v[70:71], v[2:3] op_sel_hi:[1,0] neg_lo:[0,1] neg_hi:[0,1]
	v_pk_add_f32 v[102:103], v[102:103], v[2:3] op_sel_hi:[1,0] neg_lo:[0,1] neg_hi:[0,1]
	v_pk_add_f32 v[54:55], v[54:55], v[2:3] op_sel_hi:[1,0] neg_lo:[0,1] neg_hi:[0,1]
	v_pk_add_f32 v[88:89], v[88:89], v[2:3] op_sel_hi:[1,0] neg_lo:[0,1] neg_hi:[0,1]
	v_pk_add_f32 v[72:73], v[72:73], v[2:3] op_sel_hi:[1,0] neg_lo:[0,1] neg_hi:[0,1]
	v_pk_add_f32 v[104:105], v[104:105], v[2:3] op_sel_hi:[1,0] neg_lo:[0,1] neg_hi:[0,1]
	v_pk_add_f32 v[56:57], v[56:57], v[2:3] op_sel_hi:[1,0] neg_lo:[0,1] neg_hi:[0,1]
	v_pk_add_f32 v[90:91], v[90:91], v[2:3] op_sel_hi:[1,0] neg_lo:[0,1] neg_hi:[0,1]
	v_pk_add_f32 v[74:75], v[74:75], v[2:3] op_sel_hi:[1,0] neg_lo:[0,1] neg_hi:[0,1]
	v_pk_add_f32 v[106:107], v[106:107], v[2:3] op_sel_hi:[1,0] neg_lo:[0,1] neg_hi:[0,1]
	v_pk_add_f32 v[58:59], v[58:59], v[2:3] op_sel_hi:[1,0] neg_lo:[0,1] neg_hi:[0,1]
	v_pk_add_f32 v[92:93], v[92:93], v[2:3] op_sel_hi:[1,0] neg_lo:[0,1] neg_hi:[0,1]
	v_pk_add_f32 v[76:77], v[76:77], v[2:3] op_sel_hi:[1,0] neg_lo:[0,1] neg_hi:[0,1]
	v_pk_add_f32 v[108:109], v[108:109], v[2:3] op_sel_hi:[1,0] neg_lo:[0,1] neg_hi:[0,1]
	v_pk_add_f32 v[60:61], v[60:61], v[2:3] op_sel_hi:[1,0] neg_lo:[0,1] neg_hi:[0,1]
	v_pk_add_f32 v[94:95], v[94:95], v[2:3] op_sel_hi:[1,0] neg_lo:[0,1] neg_hi:[0,1]
	v_pk_add_f32 v[78:79], v[78:79], v[2:3] op_sel_hi:[1,0] neg_lo:[0,1] neg_hi:[0,1]
	v_pk_add_f32 v[110:111], v[110:111], v[2:3] op_sel_hi:[1,0] neg_lo:[0,1] neg_hi:[0,1]
	v_pk_add_f32 v[62:63], v[62:63], v[2:3] op_sel_hi:[1,0] neg_lo:[0,1] neg_hi:[0,1]
	v_pk_mul_f32 v[46:47], v[46:47], v[4:5] op_sel_hi:[1,0]
	v_pk_mul_f32 v[44:45], v[44:45], v[4:5] op_sel_hi:[1,0]
	v_pk_mul_f32 v[42:43], v[42:43], v[4:5] op_sel_hi:[1,0]
	v_pk_mul_f32 v[40:41], v[40:41], v[4:5] op_sel_hi:[1,0]
	v_pk_mul_f32 v[38:39], v[38:39], v[4:5] op_sel_hi:[1,0]
	v_pk_mul_f32 v[36:37], v[36:37], v[4:5] op_sel_hi:[1,0]
	v_pk_mul_f32 v[34:35], v[34:35], v[4:5] op_sel_hi:[1,0]
	v_pk_mul_f32 v[32:33], v[32:33], v[4:5] op_sel_hi:[1,0]
	v_pk_mul_f32 v[30:31], v[30:31], v[4:5] op_sel_hi:[1,0]
	v_pk_mul_f32 v[28:29], v[28:29], v[4:5] op_sel_hi:[1,0]
	v_pk_mul_f32 v[26:27], v[26:27], v[4:5] op_sel_hi:[1,0]
	v_pk_mul_f32 v[24:25], v[24:25], v[4:5] op_sel_hi:[1,0]
	v_pk_mul_f32 v[22:23], v[22:23], v[4:5] op_sel_hi:[1,0]
	v_pk_mul_f32 v[20:21], v[20:21], v[4:5] op_sel_hi:[1,0]
	v_pk_mul_f32 v[18:19], v[18:19], v[4:5] op_sel_hi:[1,0]
	v_pk_mul_f32 v[16:17], v[16:17], v[4:5] op_sel_hi:[1,0]
	v_mul_f32_e32 v215, v215, v4
	v_xor_b32_e32 v174, 0x80000000, v0
	v_mov_b32_e32 v175, v174
	v_mov_b32_e32 v176, v174
	v_mov_b32_e32 v177, v174
	v_mov_b32_e32 v178, v174
	v_mov_b32_e32 v179, v174
	v_mov_b32_e32 v180, v174
	v_mov_b32_e32 v181, v174
	v_mov_b32_e32 v182, v174
	v_mov_b32_e32 v183, v174
	v_mov_b32_e32 v184, v174
	v_mov_b32_e32 v185, v174
	v_mov_b32_e32 v186, v174
	v_mov_b32_e32 v187, v174
	v_mov_b32_e32 v188, v174
	v_mov_b32_e32 v189, v174
.Lattn_snr_0:
	v_exp_f32_e32 v80, v80
	v_exp_f32_e32 v81, v81
	v_exp_f32_e32 v82, v82
	v_exp_f32_e32 v83, v83
	v_exp_f32_e32 v84, v84
	v_exp_f32_e32 v85, v85
	v_exp_f32_e32 v86, v86
	v_exp_f32_e32 v87, v87
	v_cvt_pk_bf16_f32 v2, v80, v81
	v_cvt_pk_bf16_f32 v3, v82, v83
	v_cvt_pk_bf16_f32 v4, v84, v85
	v_cvt_pk_bf16_f32 v5, v86, v87
	v_add_f32_e32 v12, v80, v84
	v_add_f32_e32 v13, v81, v85
	v_add_f32_e32 v14, v82, v86
	v_add_f32_e32 v15, v83, v87
	s_waitcnt lgkmcnt(6)
	v_mfma_f32_32x32x16_bf16 v[32:47], v[222:225], v[2:5], v[32:47]
	v_exp_f32_e32 v88, v88
	v_exp_f32_e32 v89, v89
	v_exp_f32_e32 v90, v90
	v_exp_f32_e32 v91, v91
	v_cvt_pk_bf16_f32 v6, v88, v89
	v_cvt_pk_bf16_f32 v7, v90, v91
	v_add_f32_e32 v12, v12, v88
	v_add_f32_e32 v13, v13, v89
	v_add_f32_e32 v14, v14, v90
	v_add_f32_e32 v15, v15, v91
	s_waitcnt lgkmcnt(5)
	v_mfma_f32_32x32x16_bf16 v[16:31], v[226:229], v[2:5], v[16:31]
	v_exp_f32_e32 v92, v92
	v_exp_f32_e32 v93, v93
	v_exp_f32_e32 v94, v94
	v_exp_f32_e32 v95, v95
	v_cvt_pk_bf16_f32 v8, v92, v93
	v_cvt_pk_bf16_f32 v9, v94, v95
	v_add_f32_e32 v12, v12, v92
	v_add_f32_e32 v13, v13, v93
	v_add_f32_e32 v14, v14, v94
	v_add_f32_e32 v15, v15, v95
	ds_read_b128 v[222:225], v238 offset:8192
	v_xor_b32_e32 v239, 128, v155
	ds_read_b128 v[226:229], v239
	s_waitcnt lgkmcnt(6)
	v_mfma_f32_32x32x16_bf16 v[32:47], v[230:233], v[6:9], v[32:47]
	v_exp_f32_e32 v64, v64
	v_exp_f32_e32 v65, v65
	v_exp_f32_e32 v66, v66
	v_exp_f32_e32 v67, v67
	v_cvt_pk_bf16_f32 v2, v64, v65
	v_cvt_pk_bf16_f32 v3, v66, v67
	v_add_f32_e32 v12, v12, v64
	v_add_f32_e32 v13, v13, v65
	v_add_f32_e32 v14, v14, v66
	v_add_f32_e32 v15, v15, v67
	s_waitcnt lgkmcnt(5)
	v_mfma_f32_32x32x16_bf16 v[16:31], v[234:237], v[6:9], v[16:31]
	v_exp_f32_e32 v68, v68
	v_exp_f32_e32 v69, v69
	v_exp_f32_e32 v70, v70
	v_exp_f32_e32 v71, v71
	v_cvt_pk_bf16_f32 v4, v68, v69
	v_cvt_pk_bf16_f32 v5, v70, v71
	v_add_f32_e32 v12, v12, v68
	v_add_f32_e32 v13, v13, v69
	v_add_f32_e32 v14, v14, v70
	v_add_f32_e32 v15, v15, v71
	ds_read_b128 v[230:233], v239 offset:8192
	v_xor_b32_e32 v238, 160, v155
	ds_read_b128 v[234:237], v238
	s_waitcnt lgkmcnt(6)
	v_mfma_f32_32x32x16_bf16 v[32:47], v[242:245], v[2:5], v[32:47]
	v_exp_f32_e32 v72, v72
	v_exp_f32_e32 v73, v73
	v_exp_f32_e32 v74, v74
	v_exp_f32_e32 v75, v75
	v_cvt_pk_bf16_f32 v6, v72, v73
	v_cvt_pk_bf16_f32 v7, v74, v75
	v_add_f32_e32 v12, v12, v72
	v_add_f32_e32 v13, v13, v73
	v_add_f32_e32 v14, v14, v74
	v_add_f32_e32 v15, v15, v75
	s_waitcnt lgkmcnt(5)
	v_mfma_f32_32x32x16_bf16 v[16:31], v[246:249], v[2:5], v[16:31]
	v_exp_f32_e32 v76, v76
	v_exp_f32_e32 v77, v77
	v_exp_f32_e32 v78, v78
	v_exp_f32_e32 v79, v79
	v_cvt_pk_bf16_f32 v8, v76, v77
	v_cvt_pk_bf16_f32 v9, v78, v79
	v_add_f32_e32 v12, v12, v76
	v_add_f32_e32 v13, v13, v77
	v_add_f32_e32 v14, v14, v78
	v_add_f32_e32 v15, v15, v79
	ds_read_b128 v[242:245], v238 offset:8192
	v_xor_b32_e32 v239, 192, v155
	ds_read_b128 v[246:249], v239
	s_waitcnt lgkmcnt(6)
	v_mfma_f32_32x32x16_bf16 v[32:47], v[250:253], v[6:9], v[32:47]
	v_exp_f32_e32 v96, v96
	v_exp_f32_e32 v97, v97
	v_exp_f32_e32 v98, v98
	v_exp_f32_e32 v99, v99
	v_cvt_pk_bf16_f32 v2, v96, v97
	v_cvt_pk_bf16_f32 v3, v98, v99
	v_add_f32_e32 v12, v12, v96
	v_add_f32_e32 v13, v13, v97
	v_add_f32_e32 v14, v14, v98
	v_add_f32_e32 v15, v15, v99
	s_waitcnt lgkmcnt(5)
	v_mfma_f32_32x32x16_bf16 v[16:31], v[222:225], v[6:9], v[16:31]
	v_exp_f32_e32 v100, v100
	v_exp_f32_e32 v101, v101
	v_exp_f32_e32 v102, v102
	v_exp_f32_e32 v103, v103
	v_cvt_pk_bf16_f32 v4, v100, v101
	v_cvt_pk_bf16_f32 v5, v102, v103
	v_add_f32_e32 v12, v12, v100
	v_add_f32_e32 v13, v13, v101
	v_add_f32_e32 v14, v14, v102
	v_add_f32_e32 v15, v15, v103
	ds_read_b128 v[250:253], v239 offset:8192
	v_xor_b32_e32 v238, 224, v155
	ds_read_b128 v[222:225], v238
	s_waitcnt lgkmcnt(6)
	v_mfma_f32_32x32x16_bf16 v[32:47], v[226:229], v[2:5], v[32:47]
	v_exp_f32_e32 v104, v104
	v_exp_f32_e32 v105, v105
	v_exp_f32_e32 v106, v106
	v_exp_f32_e32 v107, v107
	v_cvt_pk_bf16_f32 v6, v104, v105
	v_cvt_pk_bf16_f32 v7, v106, v107
	v_add_f32_e32 v12, v12, v104
	v_add_f32_e32 v13, v13, v105
	v_add_f32_e32 v14, v14, v106
	v_add_f32_e32 v15, v15, v107
	s_waitcnt lgkmcnt(5)
	v_mfma_f32_32x32x16_bf16 v[16:31], v[230:233], v[2:5], v[16:31]
	v_exp_f32_e32 v108, v108
	v_exp_f32_e32 v109, v109
	v_exp_f32_e32 v110, v110
	v_exp_f32_e32 v111, v111
	v_cvt_pk_bf16_f32 v8, v108, v109
	v_cvt_pk_bf16_f32 v9, v110, v111
	v_add_f32_e32 v12, v12, v108
	v_add_f32_e32 v13, v13, v109
	v_add_f32_e32 v14, v14, v110
	v_add_f32_e32 v15, v15, v111
	ds_read_b128 v[226:229], v238 offset:8192
	s_waitcnt lgkmcnt(5)
	v_mfma_f32_32x32x16_bf16 v[32:47], v[234:237], v[6:9], v[32:47]
	v_exp_f32_e32 v48, v48
	v_exp_f32_e32 v49, v49
	v_exp_f32_e32 v50, v50
	v_exp_f32_e32 v51, v51
	v_cvt_pk_bf16_f32 v2, v48, v49
	v_cvt_pk_bf16_f32 v3, v50, v51
	v_add_f32_e32 v12, v12, v48
	v_add_f32_e32 v13, v13, v49
	v_add_f32_e32 v14, v14, v50
	v_add_f32_e32 v15, v15, v51
	s_waitcnt lgkmcnt(4)
	v_mfma_f32_32x32x16_bf16 v[16:31], v[242:245], v[6:9], v[16:31]
	v_exp_f32_e32 v52, v52
	v_exp_f32_e32 v53, v53
	v_exp_f32_e32 v54, v54
	v_exp_f32_e32 v55, v55
	v_cvt_pk_bf16_f32 v4, v52, v53
	v_cvt_pk_bf16_f32 v5, v54, v55
	v_add_f32_e32 v12, v12, v52
	v_add_f32_e32 v13, v13, v53
	v_add_f32_e32 v14, v14, v54
	v_add_f32_e32 v15, v15, v55
	s_waitcnt lgkmcnt(3)
	v_mfma_f32_32x32x16_bf16 v[32:47], v[246:249], v[2:5], v[32:47]
	v_exp_f32_e32 v56, v56
	v_exp_f32_e32 v57, v57
	v_exp_f32_e32 v58, v58
	v_exp_f32_e32 v59, v59
	v_cvt_pk_bf16_f32 v6, v56, v57
	v_cvt_pk_bf16_f32 v7, v58, v59
	v_add_f32_e32 v12, v12, v56
	v_add_f32_e32 v13, v13, v57
	v_add_f32_e32 v14, v14, v58
	v_add_f32_e32 v15, v15, v59
	s_waitcnt lgkmcnt(2)
	v_mfma_f32_32x32x16_bf16 v[16:31], v[250:253], v[2:5], v[16:31]
	v_exp_f32_e32 v60, v60
	v_exp_f32_e32 v61, v61
	v_exp_f32_e32 v62, v62
	v_exp_f32_e32 v63, v63
	v_cvt_pk_bf16_f32 v8, v60, v61
	v_cvt_pk_bf16_f32 v9, v62, v63
	v_add_f32_e32 v12, v12, v60
	v_add_f32_e32 v13, v13, v61
	v_add_f32_e32 v14, v14, v62
	v_add_f32_e32 v15, v15, v63
	s_waitcnt lgkmcnt(1)
	v_mfma_f32_32x32x16_bf16 v[32:47], v[222:225], v[6:9], v[32:47]
	s_waitcnt lgkmcnt(0)
	v_mfma_f32_32x32x16_bf16 v[16:31], v[226:229], v[6:9], v[16:31]
	v_add_f32_e32 v12, v12, v13
	v_add_f32_e32 v14, v14, v15
	v_add_f32_e32 v12, v12, v14
	v_add_f32_e32 v215, v215, v12
	s_addk_i32 s52, 0x80
	s_mov_b32 s18, s16
	s_cmp_lt_u32 s18, s10
	s_cbranch_scc1 .LBB0_634
	s_branch .LBB0_652

.LBB0_1384:
	v_cmp_lt_i32_e32 vcc, 7, v0
	s_and_saveexec_b64 s[2:3], vcc
	s_xor_b64 s[86:87], exec, s[2:3]
	s_cbranch_execz .LBB0_1441
	v_cmp_lt_u32_e32 vcc, 15, v0
	s_and_saveexec_b64 s[2:3], vcc
	s_xor_b64 s[8:9], exec, s[2:3]
	s_cbranch_execz .LBB0_1421
	v_add_u32_e32 v2, -16, v0
	v_lshrrev_b32_e32 v2, 1, v2
	v_sub_u32_e32 v14, 31, v2
	v_mov_b32_e32 v18, v198
	v_lshlrev_b32_e32 v15, 8, v14
	v_readlane_b32 s4, v240, 36
	v_and_b32_e32 v12, 31, v18
	v_ashrrev_i32_e32 v2, 1, v18
	v_and_b32_e32 v19, 1, v0
	v_readlane_b32 s2, v240, 21
	v_and_b32_e32 v16, 0xffffffe0, v2
	v_or3_b32 v2, s4, v15, v12
	v_bitop3_b32 v4, v19, 7, s2 bitop3:0xc8
	v_add_u32_e32 v5, v2, v16
	v_mov_b64_e32 v[2:3], s[50:51]
	v_bfe_u32 v13, v18, 5, 1
	v_mad_i64_i32 v[156:157], s[2:3], v5, s61, v[2:3]
	v_lshlrev_b32_e32 v2, 7, v4
	v_mov_b32_e32 v3, v1
	v_lshl_add_u64 v[2:3], v[156:157], 0, v[2:3]
	v_lshlrev_b32_e32 v158, 4, v13
	v_mov_b32_e32 v159, v1
	v_lshl_add_u64 v[2:3], v[2:3], 0, v[158:159]
	s_mov_b64 s[2:3], 0x1000
	v_lshlrev_b32_e32 v0, 6, v4
	v_lshl_add_u64 v[4:5], v[2:3], 0, s[2:3]
	v_add_co_u32_e32 v2, vcc, s70, v2
	s_mov_b64 s[2:3], 0x1400
	s_nop 0
	v_addc_co_u32_e32 v3, vcc, 0, v3, vcc
	global_load_dwordx4 v[112:115], v[4:5], off offset:32
	global_load_dwordx4 v[116:119], v[4:5], off offset:64
	global_load_dwordx4 v[120:123], v[2:3], off
	global_load_dwordx4 v[124:127], v[4:5], off offset:96
	v_lshl_add_u64 v[2:3], v[156:157], 0, v[0:1]
	v_lshl_add_u64 v[2:3], v[2:3], 0, v[158:159]
	v_lshl_add_u64 v[4:5], v[2:3], 0, s[2:3]
	v_add_co_u32_e32 v2, vcc, s70, v2
	s_mov_b32 s2, 0x2aaaaaab
	s_nop 0
	v_addc_co_u32_e32 v3, vcc, 0, v3, vcc
	global_load_dwordx4 v[128:131], v[2:3], off offset:1024
	global_load_dwordx4 v[132:135], v[4:5], off offset:32
	v_mul_hi_i32 v2, v18, s2
	v_lshrrev_b32_e32 v3, 31, v2
	v_ashrrev_i32_e32 v2, 1, v2
	v_add_u32_e32 v17, v2, v3
	v_mul_lo_u32 v2, v17, 12
	v_sub_u32_e32 v2, v18, v2
	v_add_u32_e32 v160, s4, v17
	v_cmp_lt_i32_e64 s[2:3], 7, v2
	v_ashrrev_i32_e32 v161, 31, v160
	v_lshlrev_b32_e32 v162, 4, v2
	s_and_saveexec_b64 s[4:5], s[2:3]
	s_xor_b64 s[4:5], exec, s[4:5]
	v_mov_b64_e32 v[4:5], s[50:51]
	v_mad_i64_i32 v[4:5], s[6:7], v160, s61, v[4:5]
	v_mov_b32_e32 v163, v1
	v_lshl_add_u64 v[4:5], v[4:5], 0, v[162:163]
	v_lshl_add_u64 v[4:5], v[4:5], 0, s[84:85]
	s_or_saveexec_b64 s[4:5], s[4:5]
	v_lshlrev_b32_e32 v2, 3, v2
	v_lshlrev_b32_e32 v164, 1, v0
	v_ashrrev_i32_e32 v20, 31, v2
	s_xor_b64 exec, exec, s[4:5]
	v_lshlrev_b64 v[4:5], 10, v[160:161]
	v_lshl_add_u64 v[4:5], s[64:65], 0, v[4:5]
	v_mov_b32_e32 v165, v1
	v_lshl_add_u64 v[4:5], v[4:5], 0, v[164:165]
	v_mov_b32_e32 v3, v20
	v_lshl_add_u64 v[4:5], v[2:3], 1, v[4:5]
	s_or_b64 exec, exec, s[4:5]
	v_mov_b64_e32 v[136:137], v[4:5]
	v_lshlrev_b32_e32 v238, 2, v160
	v_and_b32_e32 v238, 0x30, v238
	v_xor_b32_e32 v136, v136, v238
	v_and_b32_e32 v239, 0x1c0, v198
	v_lshlrev_b32_e32 v239, 4, v239
	s_nop 1
	v_readfirstlane_b32 s14, v239
	s_mov_b32 m0, s14
	s_nop 0
	global_load_lds_dwordx4 v[136:137], off
	v_add_u32_e32 v3, 0x200, v18
	s_mov_b32 s4, 0x2aaaaaab
	v_mul_hi_i32 v0, v3, s4
	v_lshrrev_b32_e32 v4, 31, v0
	v_ashrrev_i32_e32 v0, 1, v0
	v_add_u32_e32 v21, v0, v4
	v_mul_lo_u32 v0, v21, 12
	v_readlane_b32 s4, v240, 36
	v_sub_u32_e32 v0, v3, v0
	v_lshlrev_b32_e32 v168, 4, v0
	v_add_u32_e32 v166, s4, v21
	v_cmp_lt_i32_e64 s[4:5], 7, v0
	v_ashrrev_i32_e32 v167, 31, v166
	s_and_saveexec_b64 s[6:7], s[4:5]
	s_xor_b64 s[6:7], exec, s[6:7]
	v_mov_b64_e32 v[4:5], s[50:51]
	v_mad_i64_i32 v[4:5], s[10:11], v166, s61, v[4:5]
	v_mov_b32_e32 v169, v1
	v_lshl_add_u64 v[4:5], v[4:5], 0, v[168:169]
	v_lshl_add_u64 v[6:7], v[4:5], 0, s[84:85]
	s_or_saveexec_b64 s[6:7], s[6:7]
	v_lshlrev_b32_e32 v4, 3, v0
	v_ashrrev_i32_e32 v22, 31, v4
	s_xor_b64 exec, exec, s[6:7]
	v_lshlrev_b64 v[6:7], 10, v[166:167]
	v_lshl_add_u64 v[6:7], s[64:65], 0, v[6:7]
	v_mov_b32_e32 v165, v1
	v_lshl_add_u64 v[6:7], v[6:7], 0, v[164:165]
	v_mov_b32_e32 v5, v22
	v_lshl_add_u64 v[6:7], v[4:5], 1, v[6:7]
	s_or_b64 exec, exec, s[6:7]
	v_mov_b64_e32 v[138:139], v[6:7]
	v_lshlrev_b32_e32 v238, 2, v166
	v_and_b32_e32 v238, 0x30, v238
	v_xor_b32_e32 v138, v138, v238
	v_and_b32_e32 v239, 0x1c0, v198
	v_lshlrev_b32_e32 v239, 4, v239
	v_add_u32_e32 v239, 0x2000, v239
	s_nop 1
	v_readfirstlane_b32 s14, v239
	s_mov_b32 m0, s14
	s_nop 0
	global_load_lds_dwordx4 v[138:139], off
	v_add_u32_e32 v0, 0x400, v18
	s_mov_b32 s6, 0x2aaaaaab
	v_mul_hi_i32 v5, v0, s6
	v_lshrrev_b32_e32 v6, 31, v5
	v_ashrrev_i32_e32 v5, 1, v5
	v_add_u32_e32 v23, v5, v6
	v_mul_lo_u32 v5, v23, 12
	v_readlane_b32 s6, v240, 36
	v_sub_u32_e32 v5, v0, v5
	v_lshlrev_b32_e32 v0, 3, v5
	v_add_u32_e32 v170, s6, v23
	v_cmp_lt_i32_e64 s[6:7], 7, v5
	v_ashrrev_i32_e32 v171, 31, v170
	v_lshlrev_b32_e32 v172, 4, v5
	s_and_saveexec_b64 s[10:11], s[6:7]
	s_xor_b64 s[10:11], exec, s[10:11]
	v_mov_b64_e32 v[6:7], s[50:51]
	v_mad_i64_i32 v[6:7], s[12:13], v170, s61, v[6:7]
	v_mov_b32_e32 v173, v1
	v_lshl_add_u64 v[6:7], v[6:7], 0, v[172:173]
	v_lshl_add_u64 v[10:11], v[6:7], 0, s[84:85]
	v_mov_b64_e32 v[6:7], v[0:1]
	s_or_saveexec_b64 s[10:11], s[10:11]
	v_mov_b64_e32 v[8:9], v[6:7]
	s_xor_b64 exec, exec, s[10:11]
	v_lshlrev_b64 v[6:7], 10, v[170:171]
	v_lshl_add_u64 v[6:7], s[64:65], 0, v[6:7]
	v_mov_b32_e32 v165, v1
	v_lshl_add_u64 v[8:9], v[6:7], 0, v[164:165]
	v_ashrrev_i32_e32 v7, 31, v0
	v_mov_b32_e32 v6, v0
	v_lshl_add_u64 v[10:11], v[6:7], 1, v[8:9]
	v_mov_b64_e32 v[8:9], v[0:1]
	s_or_b64 exec, exec, s[10:11]
	v_readlane_b32 s10, v240, 21
	v_mov_b64_e32 v[140:141], v[10:11]
	v_lshlrev_b32_e32 v238, 2, v170
	v_and_b32_e32 v238, 0x30, v238
	v_xor_b32_e32 v140, v140, v238
	v_and_b32_e32 v239, 0x1c0, v198
	v_lshlrev_b32_e32 v239, 4, v239
	v_add_u32_e32 v239, 0x4000, v239
	s_nop 1
	v_readfirstlane_b32 s14, v239
	s_mov_b32 m0, s14
	s_nop 0
	global_load_lds_dwordx4 v[140:141], off
	v_ashrrev_i32_e32 v10, 4, v18
	v_or_b32_e32 v0, s10, v19
	v_readlane_b32 s10, v240, 47
	v_lshlrev_b32_e32 v0, 20, v0
	v_readlane_b32 s11, v240, 48
	v_ashrrev_i32_e32 v11, 31, v10
	v_lshlrev_b64 v[26:27], 14, v[10:11]
	v_lshl_add_u64 v[24:25], s[10:11], 0, v[0:1]
	v_lshlrev_b32_e32 v0, 3, v18
	v_and_b32_e32 v163, 0x78, v0
	v_ashrrev_i32_e32 v18, 4, v3
	v_lshl_add_u64 v[26:27], v[24:25], 0, v[26:27]
	v_lshlrev_b32_e32 v0, 1, v163
	v_ashrrev_i32_e32 v19, 31, v18
	v_lshl_add_u64 v[174:175], v[26:27], 0, v[0:1]
	v_lshlrev_b64 v[26:27], 14, v[18:19]
	v_lshl_add_u64 v[24:25], v[24:25], 0, v[26:27]
	v_lshl_add_u64 v[176:177], v[24:25], 0, v[0:1]
	v_mov_b64_e32 v[142:143], v[174:175]
	v_and_b32_e32 v238, 0xf0, v198
	v_xor_b32_e32 v142, v142, v238
	v_and_b32_e32 v239, 0x1c0, v198
	v_lshlrev_b32_e32 v239, 4, v239
	v_add_u32_e32 v239, 0xc000, v239
	s_nop 1
	v_readfirstlane_b32 s14, v239
	s_mov_b32 m0, s14
	s_nop 0
	global_load_lds_dwordx4 v[142:143], off
	v_mov_b64_e32 v[144:145], v[176:177]
	v_and_b32_e32 v238, 0xf0, v198
	v_xor_b32_e32 v144, v144, v238
	v_and_b32_e32 v239, 0x1c0, v198
	v_lshlrev_b32_e32 v239, 4, v239
	v_add_u32_e32 v239, 0xe000, v239
	s_nop 1
	v_readfirstlane_b32 s14, v239
	s_mov_b32 m0, s14
	s_nop 0
	global_load_lds_dwordx4 v[144:145], off
	v_add_u32_e32 v0, v16, v15
	v_and_b32_e32 v3, 64, v202
	v_or_b32_e32 v173, v0, v12
	v_xor_b32_e32 v0, 32, v202
	v_add_u32_e32 v3, 64, v3
	v_cmp_lt_i32_e32 vcc, v0, v3
	v_mov_b32_e32 v3, v1
	v_mov_b32_e32 v165, v1
	v_mov_b32_e32 v5, v1
	v_lshlrev_b32_e32 v169, 1, v14
	v_lshl_add_u64 v[178:179], v[2:3], 1, s[50:51]
	v_lshl_add_u64 v[14:15], s[64:65], 0, v[164:165]
	v_mov_b32_e32 v3, v20
	v_lshl_add_u64 v[182:183], v[4:5], 1, s[50:51]
	v_mov_b32_e32 v5, v22
	s_movk_i32 s10, 0xd0
	v_cndmask_b32_e32 v0, v202, v0, vcc
	v_lshl_add_u64 v[180:181], v[2:3], 1, v[14:15]
	v_lshl_add_u64 v[184:185], v[4:5], 1, v[14:15]
	v_lshl_add_u64 v[188:189], v[6:7], 1, v[14:15]
	v_mul_lo_u32 v165, v17, s10
	v_mul_lo_u32 v210, v21, s10
	v_mul_lo_u32 v211, v23, s10
	s_movk_i32 s10, 0x110
	v_mov_b32_e32 v14, v1
	v_mov_b32_e32 v15, v1
	v_lshlrev_b32_e32 v167, 3, v13
	v_lshlrev_b32_e32 v209, 2, v0
	v_lshl_add_u64 v[186:187], v[8:9], 1, s[50:51]
	v_lshlrev_b32_e32 v161, 2, v13
	v_mul_lo_u32 v212, v10, s10
	v_mul_lo_u32 v213, v18, s10
	v_mul_u32_u24_e32 v214, 0xd0, v12
	v_mul_u32_u24_e32 v215, 0x110, v12
	v_mov_b32_e32 v0, v1
	v_mov_b32_e32 v2, v1
	v_mov_b32_e32 v3, v1
	v_mov_b32_e32 v4, v1
	v_mov_b32_e32 v5, v1
	v_mov_b32_e32 v6, v1
	v_mov_b32_e32 v7, v1
	v_mov_b32_e32 v8, v1
	v_mov_b32_e32 v9, v1
	v_mov_b32_e32 v10, v1
	v_mov_b32_e32 v11, v1
	v_mov_b32_e32 v12, v1
	v_mov_b32_e32 v13, v1
	v_mov_b64_e32 v[30:31], v[14:15]
	v_mov_b64_e32 v[46:47], v[14:15]
	v_add_u32_e32 v171, 2, v169
	s_mov_b32 s18, 0
	v_mov_b32_e32 v159, 0
	s_movk_i32 s44, 0x80
	s_mov_b64 s[10:11], 0
	v_mov_b64_e32 v[28:29], v[12:13]
	v_mov_b64_e32 v[26:27], v[10:11]
	v_mov_b64_e32 v[24:25], v[8:9]
	v_mov_b64_e32 v[22:23], v[6:7]
	v_mov_b64_e32 v[20:21], v[4:5]
	v_mov_b64_e32 v[18:19], v[2:3]
	v_mov_b64_e32 v[16:17], v[0:1]
	v_mov_b64_e32 v[44:45], v[12:13]
	v_mov_b64_e32 v[42:43], v[10:11]
	v_mov_b64_e32 v[40:41], v[8:9]
	v_mov_b64_e32 v[38:39], v[6:7]
	v_mov_b64_e32 v[36:37], v[4:5]
	v_mov_b64_e32 v[34:35], v[2:3]
	v_mov_b64_e32 v[32:33], v[0:1]
	v_mov_b32_e32 v0, 0
	s_lshl_b32 s12, s61, 7
	v_mov_b32_e32 v238, 0x20000
	v_mov_b32_e32 v239, s12
	v_cndmask_b32_e64 v146, v238, v239, s[2:3]
	v_mov_b32_e32 v147, 0
	v_cndmask_b32_e64 v148, v238, v239, s[4:5]
	v_mov_b32_e32 v149, 0
	v_cndmask_b32_e64 v150, v238, v239, s[6:7]
	v_mov_b32_e32 v151, 0
	v_and_b32_e32 v238, 31, v198
	v_bfe_u32 v239, v198, 5, 1
	v_and_b32_e32 v152, 0x13, v238
	v_and_b32_e32 v154, 8, v238
	v_lshrrev_b32_e32 v154, 1, v154
	v_or_b32_e32 v152, v152, v154
	v_and_b32_e32 v154, 4, v238
	v_lshlrev_b32_e32 v154, 1, v154
	v_or_b32_e32 v152, v152, v154
	v_bfe_u32 v154, v152, 2, 2
	v_xor_b32_e32 v154, v154, v239
	v_mul_u32_u24_e32 v152, 0xc0, v152
	v_lshl_add_u32 v152, v154, 4, v152
	v_and_b32_e32 v154, 15, v238
	v_xor_b32_e32 v154, v154, v239
	v_lshlrev_b32_e32 v153, 8, v238
	v_lshl_add_u32 v153, v154, 4, v153
	v_xor_b32_e32 v174, 0x80000000, v0
	v_mov_b32_e32 v175, v174
	v_mov_b32_e32 v176, v174
	v_mov_b32_e32 v177, v174
	v_mov_b32_e32 v178, v174
	v_mov_b32_e32 v179, v174
	v_mov_b32_e32 v180, v174
	v_mov_b32_e32 v181, v174
	v_mov_b32_e32 v182, v174
	v_mov_b32_e32 v183, v174
	v_mov_b32_e32 v184, v174
	v_mov_b32_e32 v185, v174
	v_mov_b32_e32 v186, v174
	v_mov_b32_e32 v187, v174
	v_mov_b32_e32 v188, v174
	v_mov_b32_e32 v189, v174
	v_readfirstlane_b32 s10, v171
	v_and_b32_e32 v238, 0x1c0, v198
	v_lshlrev_b32_e32 v238, 4, v238
	s_nop 1
	v_readfirstlane_b32 s11, v238
	s_branch .LBB0_1400

.Lattn_nodma_1:
	s_add_i32 s12, s18, 2
	s_cmp_ge_u32 s12, s10
	s_cbranch_scc1 .Lattn_slow_1
	v_add_u32_e32 v10, s19, v152
	v_xor_b32_e32 v154, 32, v10
	ds_read_b128 v[6:9], v10
	ds_read_b128 v[222:225], v154
	ds_read_b128 v[226:229], v10 offset:64
	ds_read_b128 v[230:233], v154 offset:64
	ds_read_b128 v[234:237], v10 offset:128
	ds_read_b128 v[242:245], v154 offset:128
	ds_read_b128 v[246:249], v10 offset:6144
	ds_read_b128 v[250:253], v154 offset:6144
	s_waitcnt lgkmcnt(7)
	v_mfma_f32_32x32x16_bf16 v[80:95], v[6:9], v[120:123], v[174:189]
	ds_read_b128 v[6:9], v10 offset:6208
	s_waitcnt lgkmcnt(7)
	v_mfma_f32_32x32x16_bf16 v[80:95], v[222:225], v[112:115], v[80:95]
	ds_read_b128 v[222:225], v154 offset:6208
	s_waitcnt lgkmcnt(7)
	v_mfma_f32_32x32x16_bf16 v[80:95], v[226:229], v[116:119], v[80:95]
	ds_read_b128 v[226:229], v10 offset:6272
	s_waitcnt lgkmcnt(7)
	v_mfma_f32_32x32x16_bf16 v[80:95], v[230:233], v[124:127], v[80:95]
	ds_read_b128 v[230:233], v154 offset:6272
	s_waitcnt lgkmcnt(7)
	v_mfma_f32_32x32x16_bf16 v[80:95], v[234:237], v[128:131], v[80:95]
	ds_read_b128 v[234:237], v10 offset:12288
	s_waitcnt lgkmcnt(7)
	v_mfma_f32_32x32x16_bf16 v[80:95], v[242:245], v[132:135], v[80:95]
	ds_read_b128 v[242:245], v154 offset:12288
	s_waitcnt lgkmcnt(7)
	v_mfma_f32_32x32x16_bf16 v[64:79], v[246:249], v[120:123], v[174:189]
	ds_read_b128 v[246:249], v10 offset:12352
	s_waitcnt lgkmcnt(7)
	v_mfma_f32_32x32x16_bf16 v[64:79], v[250:253], v[112:115], v[64:79]
	ds_read_b128 v[250:253], v154 offset:12352
	s_waitcnt lgkmcnt(7)
	v_mfma_f32_32x32x16_bf16 v[64:79], v[6:9], v[116:119], v[64:79]
	ds_read_b128 v[6:9], v10 offset:12416
	s_waitcnt lgkmcnt(7)
	v_mfma_f32_32x32x16_bf16 v[64:79], v[222:225], v[124:127], v[64:79]
	ds_read_b128 v[222:225], v154 offset:12416
	s_waitcnt lgkmcnt(7)
	v_mfma_f32_32x32x16_bf16 v[64:79], v[226:229], v[128:131], v[64:79]
	ds_read_b128 v[226:229], v10 offset:18432
	v_max3_f32 v3, v80, v81, v82
	v_max3_f32 v3, v3, v83, v84
	v_max3_f32 v3, v3, v85, v86
	v_max3_f32 v3, v3, v87, v88
	v_max3_f32 v3, v3, v89, v90
	s_waitcnt lgkmcnt(7)
	v_mfma_f32_32x32x16_bf16 v[64:79], v[230:233], v[132:135], v[64:79]
	ds_read_b128 v[230:233], v154 offset:18432
	v_max3_f32 v3, v3, v91, v92
	v_max3_f32 v3, v3, v93, v94
	v_max_f32_e32 v3, v3, v95
	v_exp_f32_e32 v80, v80
	v_exp_f32_e32 v81, v81
	s_waitcnt lgkmcnt(7)
	v_mfma_f32_32x32x16_bf16 v[96:111], v[234:237], v[120:123], v[174:189]
	ds_read_b128 v[234:237], v10 offset:18496
	v_exp_f32_e32 v82, v82
	v_exp_f32_e32 v83, v83
	v_mov_b64_e32 v[12:13], v[80:81]
	v_mov_b64_e32 v[14:15], v[82:83]
	v_exp_f32_e32 v84, v84
	s_waitcnt lgkmcnt(7)
	v_mfma_f32_32x32x16_bf16 v[96:111], v[242:245], v[112:115], v[96:111]
	ds_read_b128 v[242:245], v154 offset:18496
	v_exp_f32_e32 v85, v85
	v_exp_f32_e32 v86, v86
	v_exp_f32_e32 v87, v87
	v_pk_add_f32 v[12:13], v[12:13], v[84:85]
	v_pk_add_f32 v[14:15], v[14:15], v[86:87]
	s_waitcnt lgkmcnt(7)
	v_mfma_f32_32x32x16_bf16 v[96:111], v[246:249], v[116:119], v[96:111]
	ds_read_b128 v[246:249], v10 offset:18560
	v_cvt_pk_bf16_f32 v80, v80, v81
	v_cvt_pk_bf16_f32 v81, v82, v83
	v_cvt_pk_bf16_f32 v82, v84, v85
	v_cvt_pk_bf16_f32 v83, v86, v87
	v_exp_f32_e32 v88, v88
	s_waitcnt lgkmcnt(7)
	v_mfma_f32_32x32x16_bf16 v[96:111], v[250:253], v[124:127], v[96:111]
	ds_read_b128 v[250:253], v154 offset:18560
	v_exp_f32_e32 v89, v89
	v_exp_f32_e32 v90, v90
	v_exp_f32_e32 v91, v91
	v_pk_add_f32 v[12:13], v[12:13], v[88:89]
	v_pk_add_f32 v[14:15], v[14:15], v[90:91]
	s_waitcnt lgkmcnt(7)
	v_mfma_f32_32x32x16_bf16 v[96:111], v[6:9], v[128:131], v[96:111]
	v_add_u32_e32 v155, s17, v153
	v_exp_f32_e32 v92, v92
	v_exp_f32_e32 v93, v93
	v_exp_f32_e32 v94, v94
	v_exp_f32_e32 v95, v95
	v_pk_add_f32 v[12:13], v[12:13], v[92:93]
	s_waitcnt lgkmcnt(6)
	v_mfma_f32_32x32x16_bf16 v[96:111], v[222:225], v[132:135], v[96:111]
	ds_read_b128 v[222:225], v155
	v_pk_add_f32 v[14:15], v[14:15], v[94:95]
	v_cvt_pk_bf16_f32 v84, v88, v89
	v_cvt_pk_bf16_f32 v85, v90, v91
	v_cvt_pk_bf16_f32 v86, v92, v93
	v_cvt_pk_bf16_f32 v87, v94, v95
	s_waitcnt lgkmcnt(6)
	v_mfma_f32_32x32x16_bf16 v[48:63], v[226:229], v[120:123], v[174:189]
	ds_read_b128 v[226:229], v155 offset:8192
	v_max3_f32 v4, v64, v65, v66
	v_max3_f32 v4, v4, v67, v68
	v_max3_f32 v4, v4, v69, v70
	v_max3_f32 v4, v4, v71, v72
	v_max3_f32 v4, v4, v73, v74
	s_waitcnt lgkmcnt(6)
	v_mfma_f32_32x32x16_bf16 v[48:63], v[230:233], v[112:115], v[48:63]
	v_xor_b32_e32 v238, 32, v155
	ds_read_b128 v[230:233], v238
	v_max3_f32 v4, v4, v75, v76
	v_max3_f32 v4, v4, v77, v78
	v_max_f32_e32 v4, v4, v79
	v_exp_f32_e32 v64, v64
	v_exp_f32_e32 v65, v65
	s_waitcnt lgkmcnt(6)
	v_mfma_f32_32x32x16_bf16 v[48:63], v[234:237], v[116:119], v[48:63]
	ds_read_b128 v[234:237], v238 offset:8192
	v_exp_f32_e32 v66, v66
	v_exp_f32_e32 v67, v67
	v_pk_add_f32 v[12:13], v[12:13], v[64:65]
	v_pk_add_f32 v[14:15], v[14:15], v[66:67]
	v_exp_f32_e32 v68, v68
	s_waitcnt lgkmcnt(6)
	v_mfma_f32_32x32x16_bf16 v[48:63], v[242:245], v[124:127], v[48:63]
	v_xor_b32_e32 v239, 64, v155
	ds_read_b128 v[242:245], v239
	v_exp_f32_e32 v69, v69
	v_exp_f32_e32 v70, v70
	v_exp_f32_e32 v71, v71
	v_pk_add_f32 v[12:13], v[12:13], v[68:69]
	v_pk_add_f32 v[14:15], v[14:15], v[70:71]
	s_waitcnt lgkmcnt(6)
	v_mfma_f32_32x32x16_bf16 v[48:63], v[246:249], v[128:131], v[48:63]
	ds_read_b128 v[246:249], v239 offset:8192
	v_cvt_pk_bf16_f32 v64, v64, v65
	v_cvt_pk_bf16_f32 v65, v66, v67
	v_cvt_pk_bf16_f32 v66, v68, v69
	v_cvt_pk_bf16_f32 v67, v70, v71
	v_exp_f32_e32 v72, v72
	s_waitcnt lgkmcnt(6)
	v_mfma_f32_32x32x16_bf16 v[48:63], v[250:253], v[132:135], v[48:63]
	v_xor_b32_e32 v238, 96, v155
	ds_read_b128 v[250:253], v238
	v_exp_f32_e32 v73, v73
	v_exp_f32_e32 v74, v74
	v_exp_f32_e32 v75, v75
	v_pk_add_f32 v[12:13], v[12:13], v[72:73]
	v_pk_add_f32 v[14:15], v[14:15], v[74:75]
	s_waitcnt lgkmcnt(6)
	v_mfma_f32_32x32x16_bf16 v[32:47], v[222:225], v[80:83], v[32:47]
	v_exp_f32_e32 v76, v76
	v_exp_f32_e32 v77, v77
	v_exp_f32_e32 v78, v78
	s_waitcnt lgkmcnt(5)
	v_mfma_f32_32x32x16_bf16 v[16:31], v[226:229], v[80:83], v[16:31]
	ds_read_b128 v[222:225], v238 offset:8192
	v_xor_b32_e32 v239, 128, v155
	ds_read_b128 v[226:229], v239
	v_exp_f32_e32 v79, v79
	v_pk_add_f32 v[12:13], v[12:13], v[76:77]
	v_pk_add_f32 v[14:15], v[14:15], v[78:79]
	s_waitcnt lgkmcnt(6)
	v_mfma_f32_32x32x16_bf16 v[32:47], v[230:233], v[84:87], v[32:47]
	v_cvt_pk_bf16_f32 v68, v72, v73
	v_cvt_pk_bf16_f32 v69, v74, v75
	v_cvt_pk_bf16_f32 v70, v76, v77
	s_waitcnt lgkmcnt(5)
	v_mfma_f32_32x32x16_bf16 v[16:31], v[234:237], v[84:87], v[16:31]
	ds_read_b128 v[230:233], v239 offset:8192
	v_xor_b32_e32 v238, 160, v155
	ds_read_b128 v[234:237], v238
	v_cvt_pk_bf16_f32 v71, v78, v79
	s_waitcnt lgkmcnt(6)
	v_mfma_f32_32x32x16_bf16 v[32:47], v[242:245], v[64:67], v[32:47]
	v_max3_f32 v5, v96, v97, v98
	v_max3_f32 v5, v5, v99, v100
	v_max3_f32 v5, v5, v101, v102
	v_max3_f32 v5, v5, v103, v104
	v_max3_f32 v5, v5, v105, v106
	v_max3_f32 v5, v5, v107, v108
	v_max3_f32 v5, v5, v109, v110
	v_max_f32_e32 v5, v5, v111
	v_exp_f32_e32 v96, v96
	v_exp_f32_e32 v97, v97
	s_waitcnt lgkmcnt(5)
	v_mfma_f32_32x32x16_bf16 v[16:31], v[246:249], v[64:67], v[16:31]
	ds_read_b128 v[242:245], v238 offset:8192
	v_xor_b32_e32 v239, 192, v155
	ds_read_b128 v[246:249], v239
	v_exp_f32_e32 v98, v98
	v_exp_f32_e32 v99, v99
	v_pk_add_f32 v[12:13], v[12:13], v[96:97]
	v_pk_add_f32 v[14:15], v[14:15], v[98:99]
	v_exp_f32_e32 v100, v100
	v_exp_f32_e32 v101, v101
	v_exp_f32_e32 v102, v102
	v_exp_f32_e32 v103, v103
	v_pk_add_f32 v[12:13], v[12:13], v[100:101]
	v_pk_add_f32 v[14:15], v[14:15], v[102:103]
	s_waitcnt lgkmcnt(6)
	v_mfma_f32_32x32x16_bf16 v[32:47], v[250:253], v[68:71], v[32:47]
	v_cvt_pk_bf16_f32 v96, v96, v97
	v_cvt_pk_bf16_f32 v97, v98, v99
	v_cvt_pk_bf16_f32 v98, v100, v101
	v_cvt_pk_bf16_f32 v99, v102, v103
	v_exp_f32_e32 v104, v104
	v_exp_f32_e32 v105, v105
	v_exp_f32_e32 v106, v106
	v_exp_f32_e32 v107, v107
	v_pk_add_f32 v[12:13], v[12:13], v[104:105]
	v_pk_add_f32 v[14:15], v[14:15], v[106:107]
	s_waitcnt lgkmcnt(5)
	v_mfma_f32_32x32x16_bf16 v[16:31], v[222:225], v[68:71], v[16:31]
	ds_read_b128 v[250:253], v239 offset:8192
	v_xor_b32_e32 v238, 224, v155
	ds_read_b128 v[222:225], v238
	v_exp_f32_e32 v108, v108
	v_exp_f32_e32 v109, v109
	v_exp_f32_e32 v110, v110
	v_exp_f32_e32 v111, v111
	v_pk_add_f32 v[12:13], v[12:13], v[108:109]
	v_pk_add_f32 v[14:15], v[14:15], v[110:111]
	v_cvt_pk_bf16_f32 v100, v104, v105
	v_cvt_pk_bf16_f32 v101, v106, v107
	v_cvt_pk_bf16_f32 v102, v108, v109
	v_cvt_pk_bf16_f32 v103, v110, v111
	s_waitcnt lgkmcnt(6)
	v_mfma_f32_32x32x16_bf16 v[32:47], v[226:229], v[96:99], v[32:47]
	v_max3_f32 v2, v48, v49, v50
	v_max3_f32 v2, v2, v51, v52
	v_max3_f32 v2, v2, v53, v54
	v_max3_f32 v2, v2, v55, v56
	v_max3_f32 v2, v2, v57, v58
	v_max3_f32 v2, v2, v59, v60
	v_max3_f32 v2, v2, v61, v62
	v_max_f32_e32 v2, v2, v63
	v_exp_f32_e32 v48, v48
	v_exp_f32_e32 v49, v49
	s_waitcnt lgkmcnt(5)
	v_mfma_f32_32x32x16_bf16 v[16:31], v[230:233], v[96:99], v[16:31]
	ds_read_b128 v[226:229], v238 offset:8192
	v_exp_f32_e32 v50, v50
	v_exp_f32_e32 v51, v51
	v_pk_add_f32 v[12:13], v[12:13], v[48:49]
	v_pk_add_f32 v[14:15], v[14:15], v[50:51]
	v_exp_f32_e32 v52, v52
	v_exp_f32_e32 v53, v53
	v_exp_f32_e32 v54, v54
	v_exp_f32_e32 v55, v55
	v_pk_add_f32 v[12:13], v[12:13], v[52:53]
	v_pk_add_f32 v[14:15], v[14:15], v[54:55]
	s_waitcnt lgkmcnt(5)
	v_mfma_f32_32x32x16_bf16 v[32:47], v[234:237], v[100:103], v[32:47]
	v_cvt_pk_bf16_f32 v48, v48, v49
	v_cvt_pk_bf16_f32 v49, v50, v51
	v_cvt_pk_bf16_f32 v50, v52, v53
	v_cvt_pk_bf16_f32 v51, v54, v55
	v_exp_f32_e32 v56, v56
	v_exp_f32_e32 v57, v57
	v_exp_f32_e32 v58, v58
	v_exp_f32_e32 v59, v59
	v_pk_add_f32 v[12:13], v[12:13], v[56:57]
	v_pk_add_f32 v[14:15], v[14:15], v[58:59]
	s_waitcnt lgkmcnt(4)
	v_mfma_f32_32x32x16_bf16 v[16:31], v[242:245], v[100:103], v[16:31]
	v_exp_f32_e32 v60, v60
	v_exp_f32_e32 v61, v61
	v_exp_f32_e32 v62, v62
	v_exp_f32_e32 v63, v63
	v_pk_add_f32 v[12:13], v[12:13], v[60:61]
	v_pk_add_f32 v[14:15], v[14:15], v[62:63]
	v_cvt_pk_bf16_f32 v52, v56, v57
	v_cvt_pk_bf16_f32 v53, v58, v59
	v_cvt_pk_bf16_f32 v54, v60, v61
	v_cvt_pk_bf16_f32 v55, v62, v63
	s_waitcnt lgkmcnt(3)
	v_mfma_f32_32x32x16_bf16 v[32:47], v[246:249], v[48:51], v[32:47]
	s_waitcnt lgkmcnt(2)
	v_mfma_f32_32x32x16_bf16 v[16:31], v[250:253], v[48:51], v[16:31]
	s_waitcnt lgkmcnt(1)
	v_mfma_f32_32x32x16_bf16 v[32:47], v[222:225], v[52:55], v[32:47]
	s_waitcnt lgkmcnt(0)
	v_mfma_f32_32x32x16_bf16 v[16:31], v[226:229], v[52:55], v[16:31]
	v_add_f32_e32 v12, v12, v13
	v_add_f32_e32 v14, v14, v15
	v_max3_f32 v2, v2, v3, v4
	v_add_f32_e32 v12, v12, v14
	v_max_f32_e32 v2, v2, v5
	v_add_f32_e32 v159, v159, v12
	v_mov_b32_e32 v3, v2
	s_nop 1
	v_permlane32_swap_b32_e32 v2, v3
	v_max_f32_e32 v2, v2, v3
	v_cmp_lt_f32_e32 vcc, 0, v2
	s_cbranch_vccz .Lattn_fnr_1
	s_nop 7
	s_nop 3
	v_max_f32_e32 v2, 0, v2
	v_exp_f32_e64 v4, -v2
	v_add_f32_e32 v0, v0, v2
	s_nop 0
	v_mul_f32_e32 v159, v159, v4
	v_mul_f32_e32 v16, v16, v4
	v_mul_f32_e32 v17, v17, v4
	v_mul_f32_e32 v18, v18, v4
	v_mul_f32_e32 v19, v19, v4
	v_mul_f32_e32 v20, v20, v4
	v_mul_f32_e32 v21, v21, v4
	v_mul_f32_e32 v22, v22, v4
	v_mul_f32_e32 v23, v23, v4
	v_mul_f32_e32 v24, v24, v4
	v_mul_f32_e32 v25, v25, v4
	v_mul_f32_e32 v26, v26, v4
	v_mul_f32_e32 v27, v27, v4
	v_mul_f32_e32 v28, v28, v4
	v_mul_f32_e32 v29, v29, v4
	v_mul_f32_e32 v30, v30, v4
	v_mul_f32_e32 v31, v31, v4
	v_mul_f32_e32 v32, v32, v4
	v_mul_f32_e32 v33, v33, v4
	v_mul_f32_e32 v34, v34, v4
	v_mul_f32_e32 v35, v35, v4
	v_mul_f32_e32 v36, v36, v4
	v_mul_f32_e32 v37, v37, v4
	v_mul_f32_e32 v38, v38, v4
	v_mul_f32_e32 v39, v39, v4
	v_mul_f32_e32 v40, v40, v4
	v_mul_f32_e32 v41, v41, v4
	v_mul_f32_e32 v42, v42, v4
	v_mul_f32_e32 v43, v43, v4
	v_mul_f32_e32 v44, v44, v4
	v_mul_f32_e32 v45, v45, v4
	v_mul_f32_e32 v46, v46, v4
	v_mul_f32_e32 v47, v47, v4
	v_xor_b32_e32 v174, 0x80000000, v0
	v_mov_b32_e32 v175, v174
	v_mov_b32_e32 v176, v174
	v_mov_b32_e32 v177, v174
	v_mov_b32_e32 v178, v174
	v_mov_b32_e32 v179, v174
	v_mov_b32_e32 v180, v174
	v_mov_b32_e32 v181, v174
	v_mov_b32_e32 v182, v174
	v_mov_b32_e32 v183, v174
	v_mov_b32_e32 v184, v174
	v_mov_b32_e32 v185, v174
	v_mov_b32_e32 v186, v174
	v_mov_b32_e32 v187, v174
	v_mov_b32_e32 v188, v174
	v_mov_b32_e32 v189, v174
.Lattn_fnr_1:
	s_addk_i32 s44, 0x80
	s_mov_b32 s18, s16
	s_cmp_lt_u32 s18, s10
	s_cbranch_scc1 .LBB0_1400
	s_branch .LBB0_1418
.Lattn_slow_1:
	v_add_u32_e32 v10, s19, v152
	v_xor_b32_e32 v154, 32, v10
	ds_read_b128 v[6:9], v10
	ds_read_b128 v[222:225], v154
	ds_read_b128 v[226:229], v10 offset:64
	ds_read_b128 v[230:233], v154 offset:64
	ds_read_b128 v[234:237], v10 offset:128
	ds_read_b128 v[242:245], v154 offset:128
	ds_read_b128 v[246:249], v10 offset:6144
	ds_read_b128 v[250:253], v154 offset:6144
	s_waitcnt lgkmcnt(7)
	v_mfma_f32_32x32x16_bf16 v[80:95], v[6:9], v[120:123], v[174:189]
	ds_read_b128 v[6:9], v10 offset:6208
	s_waitcnt lgkmcnt(7)
	v_mfma_f32_32x32x16_bf16 v[80:95], v[222:225], v[112:115], v[80:95]
	ds_read_b128 v[222:225], v154 offset:6208
	s_waitcnt lgkmcnt(7)
	v_mfma_f32_32x32x16_bf16 v[80:95], v[226:229], v[116:119], v[80:95]
	ds_read_b128 v[226:229], v10 offset:6272
	s_waitcnt lgkmcnt(7)
	v_mfma_f32_32x32x16_bf16 v[80:95], v[230:233], v[124:127], v[80:95]
	ds_read_b128 v[230:233], v154 offset:6272
	s_waitcnt lgkmcnt(7)
	v_mfma_f32_32x32x16_bf16 v[80:95], v[234:237], v[128:131], v[80:95]
	ds_read_b128 v[234:237], v10 offset:12288
	s_waitcnt lgkmcnt(7)
	v_mfma_f32_32x32x16_bf16 v[80:95], v[242:245], v[132:135], v[80:95]
	ds_read_b128 v[242:245], v154 offset:12288
	s_waitcnt lgkmcnt(7)
	v_mfma_f32_32x32x16_bf16 v[64:79], v[246:249], v[120:123], v[174:189]
	ds_read_b128 v[246:249], v10 offset:12352
	s_waitcnt lgkmcnt(7)
	v_mfma_f32_32x32x16_bf16 v[64:79], v[250:253], v[112:115], v[64:79]
	ds_read_b128 v[250:253], v154 offset:12352
	s_waitcnt lgkmcnt(7)
	v_mfma_f32_32x32x16_bf16 v[64:79], v[6:9], v[116:119], v[64:79]
	ds_read_b128 v[6:9], v10 offset:12416
	s_waitcnt lgkmcnt(7)
	v_mfma_f32_32x32x16_bf16 v[64:79], v[222:225], v[124:127], v[64:79]
	ds_read_b128 v[222:225], v154 offset:12416
	s_waitcnt lgkmcnt(7)
	v_mfma_f32_32x32x16_bf16 v[64:79], v[226:229], v[128:131], v[64:79]
	ds_read_b128 v[226:229], v10 offset:18432
	s_waitcnt lgkmcnt(7)
	v_mfma_f32_32x32x16_bf16 v[64:79], v[230:233], v[132:135], v[64:79]
	ds_read_b128 v[230:233], v154 offset:18432
	s_waitcnt lgkmcnt(7)
	v_mfma_f32_32x32x16_bf16 v[96:111], v[234:237], v[120:123], v[174:189]
	ds_read_b128 v[234:237], v10 offset:18496
	s_waitcnt lgkmcnt(7)
	v_mfma_f32_32x32x16_bf16 v[96:111], v[242:245], v[112:115], v[96:111]
	ds_read_b128 v[242:245], v154 offset:18496
	s_waitcnt lgkmcnt(7)
	v_mfma_f32_32x32x16_bf16 v[96:111], v[246:249], v[116:119], v[96:111]
	ds_read_b128 v[246:249], v10 offset:18560
	s_waitcnt lgkmcnt(7)
	v_mfma_f32_32x32x16_bf16 v[96:111], v[250:253], v[124:127], v[96:111]
	ds_read_b128 v[250:253], v154 offset:18560
	s_waitcnt lgkmcnt(7)
	v_mfma_f32_32x32x16_bf16 v[96:111], v[6:9], v[128:131], v[96:111]
	s_waitcnt lgkmcnt(6)
	v_mfma_f32_32x32x16_bf16 v[96:111], v[222:225], v[132:135], v[96:111]
	s_waitcnt lgkmcnt(5)
	v_mfma_f32_32x32x16_bf16 v[48:63], v[226:229], v[120:123], v[174:189]
	s_waitcnt lgkmcnt(4)
	v_mfma_f32_32x32x16_bf16 v[48:63], v[230:233], v[112:115], v[48:63]
	s_waitcnt lgkmcnt(3)
	v_mfma_f32_32x32x16_bf16 v[48:63], v[234:237], v[116:119], v[48:63]
	s_waitcnt lgkmcnt(2)
	v_mfma_f32_32x32x16_bf16 v[48:63], v[242:245], v[124:127], v[48:63]
	s_waitcnt lgkmcnt(1)
	v_mfma_f32_32x32x16_bf16 v[48:63], v[246:249], v[128:131], v[48:63]
	s_waitcnt lgkmcnt(0)
	v_mfma_f32_32x32x16_bf16 v[48:63], v[250:253], v[132:135], v[48:63]
	v_add_u32_e32 v155, s17, v153
	ds_read_b128 v[222:225], v155
	ds_read_b128 v[226:229], v155 offset:8192
	v_xor_b32_e32 v238, 32, v155
	ds_read_b128 v[230:233], v238
	ds_read_b128 v[234:237], v238 offset:8192
	v_xor_b32_e32 v239, 64, v155
	ds_read_b128 v[242:245], v239
	ds_read_b128 v[246:249], v239 offset:8192
	v_xor_b32_e32 v238, 96, v155
	ds_read_b128 v[250:253], v238
	v_bfe_u32 v2, v198, 5, 1
	v_lshl_add_u32 v2, v2, 3, s44
	v_sub_u32_e32 v2, v173, v2
	v_add_u32_e32 v2, 0x80, v2
	v_add_u32_e32 v3, 0, v2
	v_cmp_le_i32_e64 vcc, 0, v3
	v_cmp_le_i32_e64 s[12:13], 1, v3
	v_cmp_le_i32_e64 s[14:15], 2, v3
	v_cndmask_b32_e64 v80, v203, v80, vcc
	v_cmp_le_i32_e64 vcc, 3, v3
	v_cndmask_b32_e64 v81, v203, v81, s[12:13]
	v_cmp_le_i32_e64 s[12:13], 4, v3
	v_cndmask_b32_e64 v82, v203, v82, s[14:15]
	v_cmp_le_i32_e64 s[14:15], 5, v3
	v_cndmask_b32_e64 v83, v203, v83, vcc
	v_cmp_le_i32_e64 vcc, 6, v3
	v_cndmask_b32_e64 v84, v203, v84, s[12:13]
	v_cmp_le_i32_e64 s[12:13], 7, v3
	v_cndmask_b32_e64 v85, v203, v85, s[14:15]
	v_add_u32_e32 v4, -16, v2
	v_cmp_le_i32_e64 s[14:15], 0, v4
	v_cndmask_b32_e64 v86, v203, v86, vcc
	v_cmp_le_i32_e64 vcc, 1, v4
	v_cndmask_b32_e64 v87, v203, v87, s[12:13]
	v_cmp_le_i32_e64 s[12:13], 2, v4
	v_cndmask_b32_e64 v88, v203, v88, s[14:15]
	v_cmp_le_i32_e64 s[14:15], 3, v4
	v_cndmask_b32_e64 v89, v203, v89, vcc
	v_cmp_le_i32_e64 vcc, 4, v4
	v_cndmask_b32_e64 v90, v203, v90, s[12:13]
	v_cmp_le_i32_e64 s[12:13], 5, v4
	v_cndmask_b32_e64 v91, v203, v91, s[14:15]
	v_cmp_le_i32_e64 s[14:15], 6, v4
	v_cndmask_b32_e64 v92, v203, v92, vcc
	v_cmp_le_i32_e64 vcc, 7, v4
	v_cndmask_b32_e64 v93, v203, v93, s[12:13]
	v_add_u32_e32 v3, 0xffffffe0, v2
	v_cmp_le_i32_e64 s[12:13], 0, v3
	v_cndmask_b32_e64 v94, v203, v94, s[14:15]
	v_cmp_le_i32_e64 s[14:15], 1, v3
	v_cndmask_b32_e64 v95, v203, v95, vcc
	v_cmp_le_i32_e64 vcc, 2, v3
	v_cndmask_b32_e64 v64, v203, v64, s[12:13]
	v_cmp_le_i32_e64 s[12:13], 3, v3
	v_cndmask_b32_e64 v65, v203, v65, s[14:15]
	v_cmp_le_i32_e64 s[14:15], 4, v3
	v_cndmask_b32_e64 v66, v203, v66, vcc
	v_cmp_le_i32_e64 vcc, 5, v3
	v_cndmask_b32_e64 v67, v203, v67, s[12:13]
	v_cmp_le_i32_e64 s[12:13], 6, v3
	v_cndmask_b32_e64 v68, v203, v68, s[14:15]
	v_cmp_le_i32_e64 s[14:15], 7, v3
	v_cndmask_b32_e64 v69, v203, v69, vcc
	v_add_u32_e32 v4, 0xffffffd0, v2
	v_cmp_le_i32_e64 vcc, 0, v4
	v_cndmask_b32_e64 v70, v203, v70, s[12:13]
	v_cmp_le_i32_e64 s[12:13], 1, v4
	v_cndmask_b32_e64 v71, v203, v71, s[14:15]
	v_cmp_le_i32_e64 s[14:15], 2, v4
	v_cndmask_b32_e64 v72, v203, v72, vcc
	v_cmp_le_i32_e64 vcc, 3, v4
	v_cndmask_b32_e64 v73, v203, v73, s[12:13]
	v_cmp_le_i32_e64 s[12:13], 4, v4
	v_cndmask_b32_e64 v74, v203, v74, s[14:15]
	v_cmp_le_i32_e64 s[14:15], 5, v4
	v_cndmask_b32_e64 v75, v203, v75, vcc
	v_cmp_le_i32_e64 vcc, 6, v4
	v_cndmask_b32_e64 v76, v203, v76, s[12:13]
	v_cmp_le_i32_e64 s[12:13], 7, v4
	v_cndmask_b32_e64 v77, v203, v77, s[14:15]
	v_add_u32_e32 v3, 0xffffffc0, v2
	v_cmp_le_i32_e64 s[14:15], 0, v3
	v_cndmask_b32_e64 v78, v203, v78, vcc
	v_cmp_le_i32_e64 vcc, 1, v3
	v_cndmask_b32_e64 v79, v203, v79, s[12:13]
	v_cmp_le_i32_e64 s[12:13], 2, v3
	v_cndmask_b32_e64 v96, v203, v96, s[14:15]
	v_cmp_le_i32_e64 s[14:15], 3, v3
	v_cndmask_b32_e64 v97, v203, v97, vcc
	v_cmp_le_i32_e64 vcc, 4, v3
	v_cndmask_b32_e64 v98, v203, v98, s[12:13]
	v_cmp_le_i32_e64 s[12:13], 5, v3
	v_cndmask_b32_e64 v99, v203, v99, s[14:15]
	v_cmp_le_i32_e64 s[14:15], 6, v3
	v_cndmask_b32_e64 v100, v203, v100, vcc
	v_cmp_le_i32_e64 vcc, 7, v3
	v_cndmask_b32_e64 v101, v203, v101, s[12:13]
	v_add_u32_e32 v4, 0xffffffb0, v2
	v_cmp_le_i32_e64 s[12:13], 0, v4
	v_cndmask_b32_e64 v102, v203, v102, s[14:15]
	v_cmp_le_i32_e64 s[14:15], 1, v4
	v_cndmask_b32_e64 v103, v203, v103, vcc
	v_cmp_le_i32_e64 vcc, 2, v4
	v_cndmask_b32_e64 v104, v203, v104, s[12:13]
	v_cmp_le_i32_e64 s[12:13], 3, v4
	v_cndmask_b32_e64 v105, v203, v105, s[14:15]
	v_cmp_le_i32_e64 s[14:15], 4, v4
	v_cndmask_b32_e64 v106, v203, v106, vcc
	v_cmp_le_i32_e64 vcc, 5, v4
	v_cndmask_b32_e64 v107, v203, v107, s[12:13]
	v_cmp_le_i32_e64 s[12:13], 6, v4
	v_cndmask_b32_e64 v108, v203, v108, s[14:15]
	v_cmp_le_i32_e64 s[14:15], 7, v4
	v_cndmask_b32_e64 v109, v203, v109, vcc
	v_add_u32_e32 v3, 0xffffffa0, v2
	v_cmp_le_i32_e64 vcc, 0, v3
	v_cndmask_b32_e64 v110, v203, v110, s[12:13]
	v_cmp_le_i32_e64 s[12:13], 1, v3
	v_cndmask_b32_e64 v111, v203, v111, s[14:15]
	v_cmp_le_i32_e64 s[14:15], 2, v3
	v_cndmask_b32_e64 v48, v203, v48, vcc
	v_cmp_le_i32_e64 vcc, 3, v3
	v_cndmask_b32_e64 v49, v203, v49, s[12:13]
	v_cmp_le_i32_e64 s[12:13], 4, v3
	v_cndmask_b32_e64 v50, v203, v50, s[14:15]
	v_cmp_le_i32_e64 s[14:15], 5, v3
	v_cndmask_b32_e64 v51, v203, v51, vcc
	v_cmp_le_i32_e64 vcc, 6, v3
	v_cndmask_b32_e64 v52, v203, v52, s[12:13]
	v_cmp_le_i32_e64 s[12:13], 7, v3
	v_cndmask_b32_e64 v53, v203, v53, s[14:15]
	v_add_u32_e32 v4, 0xffffff90, v2
	v_cmp_le_i32_e64 s[14:15], 0, v4
	v_cndmask_b32_e64 v54, v203, v54, vcc
	v_cmp_le_i32_e64 vcc, 1, v4
	v_cndmask_b32_e64 v55, v203, v55, s[12:13]
	v_cmp_le_i32_e64 s[12:13], 2, v4
	v_cndmask_b32_e64 v56, v203, v56, s[14:15]
	v_cmp_le_i32_e64 s[14:15], 3, v4
	v_cndmask_b32_e64 v57, v203, v57, vcc
	v_cmp_le_i32_e64 vcc, 4, v4
	v_cndmask_b32_e64 v58, v203, v58, s[12:13]
	v_cmp_le_i32_e64 s[12:13], 5, v4
	v_cndmask_b32_e64 v59, v203, v59, s[14:15]
	v_cmp_le_i32_e64 s[14:15], 6, v4
	v_cndmask_b32_e64 v60, v203, v60, vcc
	v_cmp_le_i32_e64 vcc, 7, v4
	v_cndmask_b32_e64 v61, v203, v61, s[12:13]
	v_cndmask_b32_e64 v62, v203, v62, s[14:15]
	v_cndmask_b32_e64 v63, v203, v63, vcc
	v_max_f32_e32 v2, v81, v81
	v_max_f32_e32 v3, v80, v80
	v_max_f32_e32 v2, v3, v2
	v_max3_f32 v2, v2, v82, v83
	v_max3_f32 v2, v2, v84, v85
	v_max3_f32 v2, v2, v86, v87
	v_max3_f32 v2, v2, v88, v89
	v_max3_f32 v2, v2, v90, v91
	v_max3_f32 v2, v2, v92, v93
	v_max3_f32 v2, v2, v94, v95
	v_max3_f32 v2, v2, v64, v65
	v_max3_f32 v2, v2, v66, v67
	v_max3_f32 v2, v2, v68, v69
	v_max3_f32 v2, v2, v70, v71
	v_max3_f32 v2, v2, v72, v73
	v_max3_f32 v2, v2, v74, v75
	v_max3_f32 v2, v2, v76, v77
	v_max3_f32 v2, v2, v78, v79
	v_max3_f32 v2, v2, v96, v97
	v_max3_f32 v2, v2, v98, v99
	v_max3_f32 v2, v2, v100, v101
	v_max3_f32 v2, v2, v102, v103
	v_max3_f32 v2, v2, v104, v105
	v_max3_f32 v2, v2, v106, v107
	v_max3_f32 v2, v2, v108, v109
	v_max3_f32 v2, v2, v110, v111
	v_max3_f32 v2, v2, v48, v49
	v_max3_f32 v2, v2, v50, v51
	v_max3_f32 v2, v2, v52, v53
	v_max3_f32 v2, v2, v54, v55
	v_max3_f32 v2, v2, v56, v57
	v_max3_f32 v2, v2, v58, v59
	v_max3_f32 v2, v2, v60, v61
	v_max3_f32 v2, v2, v62, v63
	v_mov_b32_e32 v3, v2
	s_nop 1
	v_permlane32_swap_b32_e32 v2, v3
	v_max_f32_e32 v2, v2, v3
	v_cmp_lt_f32_e32 vcc, 0, v2
	s_cbranch_vccz .Lattn_snr_1
	v_max_f32_e32 v2, v2, v2
	v_max_f32_e32 v2, 0, v2
	v_exp_f32_e64 v4, -v2
	v_add_f32_e32 v0, v0, v2
	v_pk_add_f32 v[80:81], v[80:81], v[2:3] op_sel_hi:[1,0] neg_lo:[0,1] neg_hi:[0,1]
	v_pk_add_f32 v[64:65], v[64:65], v[2:3] op_sel_hi:[1,0] neg_lo:[0,1] neg_hi:[0,1]
	v_pk_add_f32 v[96:97], v[96:97], v[2:3] op_sel_hi:[1,0] neg_lo:[0,1] neg_hi:[0,1]
	v_pk_add_f32 v[48:49], v[48:49], v[2:3] op_sel_hi:[1,0] neg_lo:[0,1] neg_hi:[0,1]
	v_pk_add_f32 v[82:83], v[82:83], v[2:3] op_sel_hi:[1,0] neg_lo:[0,1] neg_hi:[0,1]
	v_pk_add_f32 v[66:67], v[66:67], v[2:3] op_sel_hi:[1,0] neg_lo:[0,1] neg_hi:[0,1]
	v_pk_add_f32 v[98:99], v[98:99], v[2:3] op_sel_hi:[1,0] neg_lo:[0,1] neg_hi:[0,1]
	v_pk_add_f32 v[50:51], v[50:51], v[2:3] op_sel_hi:[1,0] neg_lo:[0,1] neg_hi:[0,1]
	v_pk_add_f32 v[84:85], v[84:85], v[2:3] op_sel_hi:[1,0] neg_lo:[0,1] neg_hi:[0,1]
	v_pk_add_f32 v[68:69], v[68:69], v[2:3] op_sel_hi:[1,0] neg_lo:[0,1] neg_hi:[0,1]
	v_pk_add_f32 v[100:101], v[100:101], v[2:3] op_sel_hi:[1,0] neg_lo:[0,1] neg_hi:[0,1]
	v_pk_add_f32 v[52:53], v[52:53], v[2:3] op_sel_hi:[1,0] neg_lo:[0,1] neg_hi:[0,1]
	v_pk_add_f32 v[86:87], v[86:87], v[2:3] op_sel_hi:[1,0] neg_lo:[0,1] neg_hi:[0,1]
	v_pk_add_f32 v[70:71], v[70:71], v[2:3] op_sel_hi:[1,0] neg_lo:[0,1] neg_hi:[0,1]
	v_pk_add_f32 v[102:103], v[102:103], v[2:3] op_sel_hi:[1,0] neg_lo:[0,1] neg_hi:[0,1]
	v_pk_add_f32 v[54:55], v[54:55], v[2:3] op_sel_hi:[1,0] neg_lo:[0,1] neg_hi:[0,1]
	v_pk_add_f32 v[88:89], v[88:89], v[2:3] op_sel_hi:[1,0] neg_lo:[0,1] neg_hi:[0,1]
	v_pk_add_f32 v[72:73], v[72:73], v[2:3] op_sel_hi:[1,0] neg_lo:[0,1] neg_hi:[0,1]
	v_pk_add_f32 v[104:105], v[104:105], v[2:3] op_sel_hi:[1,0] neg_lo:[0,1] neg_hi:[0,1]
	v_pk_add_f32 v[56:57], v[56:57], v[2:3] op_sel_hi:[1,0] neg_lo:[0,1] neg_hi:[0,1]
	v_pk_add_f32 v[90:91], v[90:91], v[2:3] op_sel_hi:[1,0] neg_lo:[0,1] neg_hi:[0,1]
	v_pk_add_f32 v[74:75], v[74:75], v[2:3] op_sel_hi:[1,0] neg_lo:[0,1] neg_hi:[0,1]
	v_pk_add_f32 v[106:107], v[106:107], v[2:3] op_sel_hi:[1,0] neg_lo:[0,1] neg_hi:[0,1]
	v_pk_add_f32 v[58:59], v[58:59], v[2:3] op_sel_hi:[1,0] neg_lo:[0,1] neg_hi:[0,1]
	v_pk_add_f32 v[92:93], v[92:93], v[2:3] op_sel_hi:[1,0] neg_lo:[0,1] neg_hi:[0,1]
	v_pk_add_f32 v[76:77], v[76:77], v[2:3] op_sel_hi:[1,0] neg_lo:[0,1] neg_hi:[0,1]
	v_pk_add_f32 v[108:109], v[108:109], v[2:3] op_sel_hi:[1,0] neg_lo:[0,1] neg_hi:[0,1]
	v_pk_add_f32 v[60:61], v[60:61], v[2:3] op_sel_hi:[1,0] neg_lo:[0,1] neg_hi:[0,1]
	v_pk_add_f32 v[94:95], v[94:95], v[2:3] op_sel_hi:[1,0] neg_lo:[0,1] neg_hi:[0,1]
	v_pk_add_f32 v[78:79], v[78:79], v[2:3] op_sel_hi:[1,0] neg_lo:[0,1] neg_hi:[0,1]
	v_pk_add_f32 v[110:111], v[110:111], v[2:3] op_sel_hi:[1,0] neg_lo:[0,1] neg_hi:[0,1]
	v_pk_add_f32 v[62:63], v[62:63], v[2:3] op_sel_hi:[1,0] neg_lo:[0,1] neg_hi:[0,1]
	v_pk_mul_f32 v[46:47], v[46:47], v[4:5] op_sel_hi:[1,0]
	v_pk_mul_f32 v[44:45], v[44:45], v[4:5] op_sel_hi:[1,0]
	v_pk_mul_f32 v[42:43], v[42:43], v[4:5] op_sel_hi:[1,0]
	v_pk_mul_f32 v[40:41], v[40:41], v[4:5] op_sel_hi:[1,0]
	v_pk_mul_f32 v[38:39], v[38:39], v[4:5] op_sel_hi:[1,0]
	v_pk_mul_f32 v[36:37], v[36:37], v[4:5] op_sel_hi:[1,0]
	v_pk_mul_f32 v[34:35], v[34:35], v[4:5] op_sel_hi:[1,0]
	v_pk_mul_f32 v[32:33], v[32:33], v[4:5] op_sel_hi:[1,0]
	v_pk_mul_f32 v[30:31], v[30:31], v[4:5] op_sel_hi:[1,0]
	v_pk_mul_f32 v[28:29], v[28:29], v[4:5] op_sel_hi:[1,0]
	v_pk_mul_f32 v[26:27], v[26:27], v[4:5] op_sel_hi:[1,0]
	v_pk_mul_f32 v[24:25], v[24:25], v[4:5] op_sel_hi:[1,0]
	v_pk_mul_f32 v[22:23], v[22:23], v[4:5] op_sel_hi:[1,0]
	v_pk_mul_f32 v[20:21], v[20:21], v[4:5] op_sel_hi:[1,0]
	v_pk_mul_f32 v[18:19], v[18:19], v[4:5] op_sel_hi:[1,0]
	v_pk_mul_f32 v[16:17], v[16:17], v[4:5] op_sel_hi:[1,0]
	v_mul_f32_e32 v159, v159, v4
	v_xor_b32_e32 v174, 0x80000000, v0
	v_mov_b32_e32 v175, v174
	v_mov_b32_e32 v176, v174
	v_mov_b32_e32 v177, v174
	v_mov_b32_e32 v178, v174
	v_mov_b32_e32 v179, v174
	v_mov_b32_e32 v180, v174
	v_mov_b32_e32 v181, v174
	v_mov_b32_e32 v182, v174
	v_mov_b32_e32 v183, v174
	v_mov_b32_e32 v184, v174
	v_mov_b32_e32 v185, v174
	v_mov_b32_e32 v186, v174
	v_mov_b32_e32 v187, v174
	v_mov_b32_e32 v188, v174
	v_mov_b32_e32 v189, v174
.Lattn_snr_1:
	v_exp_f32_e32 v80, v80
	v_exp_f32_e32 v81, v81
	v_exp_f32_e32 v82, v82
	v_exp_f32_e32 v83, v83
	v_exp_f32_e32 v84, v84
	v_exp_f32_e32 v85, v85
	v_exp_f32_e32 v86, v86
	v_exp_f32_e32 v87, v87
	v_cvt_pk_bf16_f32 v2, v80, v81
	v_cvt_pk_bf16_f32 v3, v82, v83
	v_cvt_pk_bf16_f32 v4, v84, v85
	v_cvt_pk_bf16_f32 v5, v86, v87
	v_add_f32_e32 v12, v80, v84
	v_add_f32_e32 v13, v81, v85
	v_add_f32_e32 v14, v82, v86
	v_add_f32_e32 v15, v83, v87
	s_waitcnt lgkmcnt(6)
	v_mfma_f32_32x32x16_bf16 v[32:47], v[222:225], v[2:5], v[32:47]
	v_exp_f32_e32 v88, v88
	v_exp_f32_e32 v89, v89
	v_exp_f32_e32 v90, v90
	v_exp_f32_e32 v91, v91
	v_cvt_pk_bf16_f32 v6, v88, v89
	v_cvt_pk_bf16_f32 v7, v90, v91
	v_add_f32_e32 v12, v12, v88
	v_add_f32_e32 v13, v13, v89
	v_add_f32_e32 v14, v14, v90
	v_add_f32_e32 v15, v15, v91
	s_waitcnt lgkmcnt(5)
	v_mfma_f32_32x32x16_bf16 v[16:31], v[226:229], v[2:5], v[16:31]
	v_exp_f32_e32 v92, v92
	v_exp_f32_e32 v93, v93
	v_exp_f32_e32 v94, v94
	v_exp_f32_e32 v95, v95
	v_cvt_pk_bf16_f32 v8, v92, v93
	v_cvt_pk_bf16_f32 v9, v94, v95
	v_add_f32_e32 v12, v12, v92
	v_add_f32_e32 v13, v13, v93
	v_add_f32_e32 v14, v14, v94
	v_add_f32_e32 v15, v15, v95
	ds_read_b128 v[222:225], v238 offset:8192
	v_xor_b32_e32 v239, 128, v155
	ds_read_b128 v[226:229], v239
	s_waitcnt lgkmcnt(6)
	v_mfma_f32_32x32x16_bf16 v[32:47], v[230:233], v[6:9], v[32:47]
	v_exp_f32_e32 v64, v64
	v_exp_f32_e32 v65, v65
	v_exp_f32_e32 v66, v66
	v_exp_f32_e32 v67, v67
	v_cvt_pk_bf16_f32 v2, v64, v65
	v_cvt_pk_bf16_f32 v3, v66, v67
	v_add_f32_e32 v12, v12, v64
	v_add_f32_e32 v13, v13, v65
	v_add_f32_e32 v14, v14, v66
	v_add_f32_e32 v15, v15, v67
	s_waitcnt lgkmcnt(5)
	v_mfma_f32_32x32x16_bf16 v[16:31], v[234:237], v[6:9], v[16:31]
	v_exp_f32_e32 v68, v68
	v_exp_f32_e32 v69, v69
	v_exp_f32_e32 v70, v70
	v_exp_f32_e32 v71, v71
	v_cvt_pk_bf16_f32 v4, v68, v69
	v_cvt_pk_bf16_f32 v5, v70, v71
	v_add_f32_e32 v12, v12, v68
	v_add_f32_e32 v13, v13, v69
	v_add_f32_e32 v14, v14, v70
	v_add_f32_e32 v15, v15, v71
	ds_read_b128 v[230:233], v239 offset:8192
	v_xor_b32_e32 v238, 160, v155
	ds_read_b128 v[234:237], v238
	s_waitcnt lgkmcnt(6)
	v_mfma_f32_32x32x16_bf16 v[32:47], v[242:245], v[2:5], v[32:47]
	v_exp_f32_e32 v72, v72
	v_exp_f32_e32 v73, v73
	v_exp_f32_e32 v74, v74
	v_exp_f32_e32 v75, v75
	v_cvt_pk_bf16_f32 v6, v72, v73
	v_cvt_pk_bf16_f32 v7, v74, v75
	v_add_f32_e32 v12, v12, v72
	v_add_f32_e32 v13, v13, v73
	v_add_f32_e32 v14, v14, v74
	v_add_f32_e32 v15, v15, v75
	s_waitcnt lgkmcnt(5)
	v_mfma_f32_32x32x16_bf16 v[16:31], v[246:249], v[2:5], v[16:31]
	v_exp_f32_e32 v76, v76
	v_exp_f32_e32 v77, v77
	v_exp_f32_e32 v78, v78
	v_exp_f32_e32 v79, v79
	v_cvt_pk_bf16_f32 v8, v76, v77
	v_cvt_pk_bf16_f32 v9, v78, v79
	v_add_f32_e32 v12, v12, v76
	v_add_f32_e32 v13, v13, v77
	v_add_f32_e32 v14, v14, v78
	v_add_f32_e32 v15, v15, v79
	ds_read_b128 v[242:245], v238 offset:8192
	v_xor_b32_e32 v239, 192, v155
	ds_read_b128 v[246:249], v239
	s_waitcnt lgkmcnt(6)
	v_mfma_f32_32x32x16_bf16 v[32:47], v[250:253], v[6:9], v[32:47]
	v_exp_f32_e32 v96, v96
	v_exp_f32_e32 v97, v97
	v_exp_f32_e32 v98, v98
	v_exp_f32_e32 v99, v99
	v_cvt_pk_bf16_f32 v2, v96, v97
	v_cvt_pk_bf16_f32 v3, v98, v99
	v_add_f32_e32 v12, v12, v96
	v_add_f32_e32 v13, v13, v97
	v_add_f32_e32 v14, v14, v98
	v_add_f32_e32 v15, v15, v99
	s_waitcnt lgkmcnt(5)
	v_mfma_f32_32x32x16_bf16 v[16:31], v[222:225], v[6:9], v[16:31]
	v_exp_f32_e32 v100, v100
	v_exp_f32_e32 v101, v101
	v_exp_f32_e32 v102, v102
	v_exp_f32_e32 v103, v103
	v_cvt_pk_bf16_f32 v4, v100, v101
	v_cvt_pk_bf16_f32 v5, v102, v103
	v_add_f32_e32 v12, v12, v100
	v_add_f32_e32 v13, v13, v101
	v_add_f32_e32 v14, v14, v102
	v_add_f32_e32 v15, v15, v103
	ds_read_b128 v[250:253], v239 offset:8192
	v_xor_b32_e32 v238, 224, v155
	ds_read_b128 v[222:225], v238
	s_waitcnt lgkmcnt(6)
	v_mfma_f32_32x32x16_bf16 v[32:47], v[226:229], v[2:5], v[32:47]
	v_exp_f32_e32 v104, v104
	v_exp_f32_e32 v105, v105
	v_exp_f32_e32 v106, v106
	v_exp_f32_e32 v107, v107
	v_cvt_pk_bf16_f32 v6, v104, v105
	v_cvt_pk_bf16_f32 v7, v106, v107
	v_add_f32_e32 v12, v12, v104
	v_add_f32_e32 v13, v13, v105
	v_add_f32_e32 v14, v14, v106
	v_add_f32_e32 v15, v15, v107
	s_waitcnt lgkmcnt(5)
	v_mfma_f32_32x32x16_bf16 v[16:31], v[230:233], v[2:5], v[16:31]
	v_exp_f32_e32 v108, v108
	v_exp_f32_e32 v109, v109
	v_exp_f32_e32 v110, v110
	v_exp_f32_e32 v111, v111
	v_cvt_pk_bf16_f32 v8, v108, v109
	v_cvt_pk_bf16_f32 v9, v110, v111
	v_add_f32_e32 v12, v12, v108
	v_add_f32_e32 v13, v13, v109
	v_add_f32_e32 v14, v14, v110
	v_add_f32_e32 v15, v15, v111
	ds_read_b128 v[226:229], v238 offset:8192
	s_waitcnt lgkmcnt(5)
	v_mfma_f32_32x32x16_bf16 v[32:47], v[234:237], v[6:9], v[32:47]
	v_exp_f32_e32 v48, v48
	v_exp_f32_e32 v49, v49
	v_exp_f32_e32 v50, v50
	v_exp_f32_e32 v51, v51
	v_cvt_pk_bf16_f32 v2, v48, v49
	v_cvt_pk_bf16_f32 v3, v50, v51
	v_add_f32_e32 v12, v12, v48
	v_add_f32_e32 v13, v13, v49
	v_add_f32_e32 v14, v14, v50
	v_add_f32_e32 v15, v15, v51
	s_waitcnt lgkmcnt(4)
	v_mfma_f32_32x32x16_bf16 v[16:31], v[242:245], v[6:9], v[16:31]
	v_exp_f32_e32 v52, v52
	v_exp_f32_e32 v53, v53
	v_exp_f32_e32 v54, v54
	v_exp_f32_e32 v55, v55
	v_cvt_pk_bf16_f32 v4, v52, v53
	v_cvt_pk_bf16_f32 v5, v54, v55
	v_add_f32_e32 v12, v12, v52
	v_add_f32_e32 v13, v13, v53
	v_add_f32_e32 v14, v14, v54
	v_add_f32_e32 v15, v15, v55
	s_waitcnt lgkmcnt(3)
	v_mfma_f32_32x32x16_bf16 v[32:47], v[246:249], v[2:5], v[32:47]
	v_exp_f32_e32 v56, v56
	v_exp_f32_e32 v57, v57
	v_exp_f32_e32 v58, v58
	v_exp_f32_e32 v59, v59
	v_cvt_pk_bf16_f32 v6, v56, v57
	v_cvt_pk_bf16_f32 v7, v58, v59
	v_add_f32_e32 v12, v12, v56
	v_add_f32_e32 v13, v13, v57
	v_add_f32_e32 v14, v14, v58
	v_add_f32_e32 v15, v15, v59
	s_waitcnt lgkmcnt(2)
	v_mfma_f32_32x32x16_bf16 v[16:31], v[250:253], v[2:5], v[16:31]
	v_exp_f32_e32 v60, v60
	v_exp_f32_e32 v61, v61
	v_exp_f32_e32 v62, v62
	v_exp_f32_e32 v63, v63
	v_cvt_pk_bf16_f32 v8, v60, v61
	v_cvt_pk_bf16_f32 v9, v62, v63
	v_add_f32_e32 v12, v12, v60
	v_add_f32_e32 v13, v13, v61
	v_add_f32_e32 v14, v14, v62
	v_add_f32_e32 v15, v15, v63
	s_waitcnt lgkmcnt(1)
	v_mfma_f32_32x32x16_bf16 v[32:47], v[222:225], v[6:9], v[32:47]
	s_waitcnt lgkmcnt(0)
	v_mfma_f32_32x32x16_bf16 v[16:31], v[226:229], v[6:9], v[16:31]
	v_add_f32_e32 v12, v12, v13
	v_add_f32_e32 v14, v14, v15
	v_add_f32_e32 v12, v12, v14
	v_add_f32_e32 v159, v159, v12
	s_addk_i32 s44, 0x80
	s_mov_b32 s18, s16
	s_cmp_lt_u32 s18, s10
	s_cbranch_scc1 .LBB0_1400
	s_branch .LBB0_1418

	.amdhsa_kernel _Z14fwd_megakernel6Params
		.amdhsa_group_segment_fixed_size 16384
		.amdhsa_private_segment_fixed_size 0
		.amdhsa_kernarg_size 416
		.amdhsa_user_sgpr_count 2
		.amdhsa_user_sgpr_dispatch_ptr 0
		.amdhsa_user_sgpr_queue_ptr 0
		.amdhsa_user_sgpr_kernarg_segment_ptr 1
		.amdhsa_user_sgpr_dispatch_id 0
		.amdhsa_user_sgpr_kernarg_preload_length 0
		.amdhsa_user_sgpr_kernarg_preload_offset 0
		.amdhsa_user_sgpr_private_segment_size 0
		.amdhsa_uses_dynamic_stack 0
		.amdhsa_enable_private_segment 0
		.amdhsa_system_sgpr_workgroup_id_x 1
		.amdhsa_system_sgpr_workgroup_id_y 0
		.amdhsa_system_sgpr_workgroup_id_z 0
		.amdhsa_system_sgpr_workgroup_info 0
		.amdhsa_system_vgpr_workitem_id 2
		.amdhsa_next_free_vgpr 256
		.amdhsa_next_free_sgpr 98
		.amdhsa_accum_offset 256
		.amdhsa_reserve_vcc 1
		.amdhsa_float_round_mode_32 0
		.amdhsa_float_round_mode_16_64 0
		.amdhsa_float_denorm_mode_32 3
		.amdhsa_float_denorm_mode_16_64 3
		.amdhsa_dx10_clamp 1
		.amdhsa_ieee_mode 1
		.amdhsa_fp16_overflow 0
		.amdhsa_tg_split 0
		.amdhsa_exception_fp_ieee_invalid_op 0
		.amdhsa_exception_fp_denorm_src 0
		.amdhsa_exception_fp_ieee_div_zero 0
		.amdhsa_exception_fp_ieee_overflow 0
		.amdhsa_exception_fp_ieee_underflow 0
		.amdhsa_exception_fp_ieee_inexact 0
		.amdhsa_exception_int_div_zero 0
	.end_amdhsa_kernel

amdhsa.kernels:
  - .agpr_count:     0
    .args:
      - .offset:         0
        .size:           160
        .value_kind:     by_value
      - .offset:         160
        .size:           4
        .value_kind:     hidden_block_count_x
      - .offset:         164
        .size:           4
        .value_kind:     hidden_block_count_y
      - .offset:         168
        .size:           4
        .value_kind:     hidden_block_count_z
      - .offset:         172
        .size:           2
        .value_kind:     hidden_group_size_x
      - .offset:         174
        .size:           2
        .value_kind:     hidden_group_size_y
      - .offset:         176
        .size:           2
        .value_kind:     hidden_group_size_z
      - .offset:         178
        .size:           2
        .value_kind:     hidden_remainder_x
      - .offset:         180
        .size:           2
        .value_kind:     hidden_remainder_y
      - .offset:         182
        .size:           2
        .value_kind:     hidden_remainder_z
      - .offset:         200
        .size:           8
        .value_kind:     hidden_global_offset_x
      - .offset:         208
        .size:           8
        .value_kind:     hidden_global_offset_y
      - .offset:         216
        .size:           8
        .value_kind:     hidden_global_offset_z
      - .offset:         224
        .size:           2
        .value_kind:     hidden_grid_dims
      - .offset:         248
        .size:           8
        .value_kind:     hidden_multigrid_sync_arg
      - .offset:         280
        .size:           4
        .value_kind:     hidden_dynamic_lds_size
    .group_segment_fixed_size: 16384
    .kernarg_segment_align: 8
    .kernarg_segment_size: 416
    .language:       OpenCL C
    .language_version:
      - 2
      - 0
    .max_flat_workgroup_size: 512
    .name:           _Z14fwd_megakernel6Params
    .private_segment_fixed_size: 0
    .sgpr_count:     104
    .sgpr_spill_count: 65
    .symbol:         _Z14fwd_megakernel6Params.kd
    .uniform_work_group_size: 1
    .uses_dynamic_stack: false
    .vgpr_count:     256
    .vgpr_spill_count: 0
    .wavefront_size: 64
